# GEMM main loops: per-segment s_setprio flips removed, one static priority raise for waves 4-7 at kernel entry
# baseline (speedup 1.0000x reference)
; #define LAS __attribute__((address_space(3)))
; __device__ __forceinline__ unsigned xb_add(unsigned* p, unsigned v) { return __hip_atomic_fetch_add(p, v, __ATOMIC_RELAXED, __HIP_MEMORY_SCOPE_AGENT); }
; __device__ __forceinline__ unsigned xb_xcc_id() { return (unsigned)__builtin_amdgcn_s_getreg((3 << 11) | 20) & 0xFu; }
; __device__ __forceinline__ XcdBarrier xcd_barrier_post(unsigned* bar, volatile LAS unsigned* st) {
;     XcdBarrier b; b.bar = bar; b.x = xb_xcc_id(); b.st = st;
;     if (threadIdx.x == 0) (void)xb_add(&bar[XB_XCNT(b.x)], 1u);
;     return b;
; __global__ void __launch_bounds__(NTHR, 2) fwd_megakernel(Args a) {
;     ...
;     { volatile LAS unsigned* z = (volatile LAS unsigned*)(lds + 131072); if (threadIdx.x < 64) z[threadIdx.x] = 0u; }
;     __syncthreads();
;     const XcdBarrier xbar = xcd_barrier_post((unsigned*)(ws + WS_CTL), (volatile LAS unsigned*)(lds + 131072 + 64));
.LBB0_2:
	s_load_dwordx2 s[80:81], s[22:23], 0x90
	v_and_b32_e32 v168, 0x3ff, v0
	s_nop 1
	v_readfirstlane_b32 s100, v168
	s_nop 3
	s_cmp_ge_u32 s100, 0x100
	s_cbranch_scc0 .Lprio_done
	s_setprio 1
.Lprio_done:
	v_cmp_gt_u32_e32 vcc, 64, v168
	s_and_saveexec_b64 s[0:1], vcc
	v_lshl_add_u32 v1, v168, 2, 0
	v_add_u32_e32 v1, 0x20000, v1
	v_mov_b32_e32 v2, 0
	ds_write_b32 v1, v2
	s_or_b64 exec, exec, s[0:1]
	s_waitcnt lgkmcnt(0)
	s_barrier
	s_add_u32 s2, s80, 0x24e80000
	s_getreg_b32 s0, hwreg(HW_REG_XCC_ID, 0, 4)
	s_addc_u32 s3, s81, 0
	s_and_b32 s14, s0, 15
	s_mov_b32 s87, 0
	v_cmp_eq_u32_e64 s[88:89], 0, v168
	s_lshl_b32 s15, s14, 6
	v_mov_b64_e32 v[132:133], s[80:81]
	s_and_saveexec_b64 s[0:1], s[88:89]
	s_cbranch_execz .LBB0_8
	s_mov_b64 s[6:7], exec
	v_mbcnt_lo_u32_b32 v1, s6, 0
	v_mbcnt_hi_u32_b32 v1, s7, v1
	v_cmp_eq_u32_e32 vcc, 0, v1
	v_mov_b64_e32 v[132:133], s[80:81]
	s_and_saveexec_b64 s[4:5], vcc
	s_cbranch_execz .LBB0_7
	s_lshl_b32 s9, s15, 2
	s_bcnt1_i32_b64 s6, s[6:7]
	v_mov_b32_e32 v1, s9
	v_mov_b32_e32 v2, s6
	global_atomic_add v1, v2, s[2:3] offset:1024
	s_load_dwordx2 s[6:7], s[22:23], 0x90
	s_waitcnt lgkmcnt(0)
	v_mov_b64_e32 v[132:133], s[6:7]

; #define PG8_STAGE(bufoff, gbase, voff) do { _Pragma("unroll") for (int _i = 0; _i < 2; ++_i) \
;         __builtin_amdgcn_global_load_lds((const unsigned*)((const char*)(gbase) + (voff)[_i]), (PG8_LAS unsigned*)(lds + (bufoff) + ldsw + _i * 8192), 16, 0, 0); } while (0)
; #define PG8_LDA(dst, b, h) do { _Pragma("unroll") for (int m = 0; m < 4; ++m) _Pragma("unroll") for (int k = 0; k < 2; ++k) dst[m][k] = *(const PG8_LAS bf16x8*)(lds + PG8_SA(b, h) + aoff + m * 2048 + k * 1024); } while (0)
; #define PG8_LDB(dst, b, h) do { _Pragma("unroll") for (int n = 0; n < 2; ++n) _Pragma("unroll") for (int k = 0; k < 2; ++k) dst[n][k] = *(const PG8_LAS bf16x8*)(lds + PG8_SB(b, h) + boff + n * 2048 + k * 1024); } while (0)
; #define PG8_MMA(ai, bj, At, Bt) do { __builtin_amdgcn_s_setprio(1); _Pragma("unroll") for (int m = 0; m < 4; ++m) _Pragma("unroll") for (int n = 0; n < 2; ++n) _Pragma("unroll") for (int k = 0; k < 2; ++k) \
;         acc[ai][bj][m][n] = __builtin_amdgcn_mfma_f32_16x16x32_bf16(Bt[n][k], At[m][k], acc[ai][bj][m][n], 0, 0, 0); __builtin_amdgcn_s_setprio(0); } while (0)
; #define PG8_WAIT_V(n) asm volatile("s_waitcnt vmcnt(" #n ")" ::: "memory")
; #define PG8_WAIT_L(n) asm volatile("s_waitcnt lgkmcnt(" #n ")" ::: "memory")
; #define PG8_BAR __builtin_amdgcn_s_barrier()
; #define PG8_SCHED __builtin_amdgcn_sched_barrier(0)
; template <class Epi, class Sched, bool ALIGN_EPI = false, bool SP2 = false>
; __device__ __forceinline__ void gemm_phase(PG8_LAS unsigned char* lds, const Gemm g, const Sched& S, const Epi& E) {
;     ...
;             PG8_LDB(B0, 0, 0); PG8_LDB(B1, 0, 1); PG8_SCHED; PG8_LDA(At, 0, 0); PG8_STAGE(PG8_SA(1, 1), a1 + hstep, voffA);
;             PG8_WAIT_V(8); PG8_WAIT_L(0); PG8_BAR; PG8_MMA(0, 0, At, B0); PG8_MMA(0, 1, At, B1); PG8_BAR; PG8_SCHED;
;             PG8_LDA(At, 0, 1); PG8_STAGE(PG8_SB(0, 0), b2, voffB); PG8_STAGE(PG8_SB(0, 1), b2 + hstep, voffB); PG8_STAGE(PG8_SA(0, 0), a2, voffA);
;             PG8_WAIT_V(8); PG8_WAIT_L(0); PG8_BAR; PG8_MMA(1, 0, At, B0); PG8_MMA(1, 1, At, B1); PG8_BAR; PG8_SCHED;
.LBB0_151:
	s_add_u32 s38, s46, 0xfff80080
	s_addc_u32 s39, s47, -1
	s_add_i32 s76, 0, 0x10000
	s_cmp_eq_u32 s79, 28
	s_cselect_b32 s53, s27, s39
	s_cselect_b32 s52, s97, s38
	s_cselect_b32 s51, s25, s78
	s_cselect_b32 s50, vcc_lo, vcc_hi
	s_add_i32 s20, 0, 0x14000
	v_add_u32_e32 v184, s76, v165
	v_add_u32_e32 v200, s20, v165
	ds_read_b128 v[160:163], v184
	ds_read_b128 v[176:179], v184 offset:1024
	ds_read_b128 v[180:183], v184 offset:2048
	ds_read_b128 v[184:187], v184 offset:3072
	ds_read_b128 v[188:191], v200
	ds_read_b128 v[192:195], v200 offset:1024
	ds_read_b128 v[196:199], v200 offset:2048
	ds_read_b128 v[200:203], v200 offset:3072
	v_lshl_add_u64 v[236:237], s[46:47], 0, v[156:157]
	s_add_i32 m0, s49, 0xc000
	ds_read_b128 v[204:207], v167
	ds_read_b128 v[208:211], v167 offset:1024
	ds_read_b128 v[212:215], v167 offset:2048
	ds_read_b128 v[216:219], v167 offset:3072
	ds_read_b128 v[220:223], v167 offset:4096
	ds_read_b128 v[224:227], v167 offset:5120
	ds_read_b128 v[228:231], v167 offset:6144
	ds_read_b128 v[232:235], v167 offset:7168
	global_load_lds_dwordx4 v[236:237], off
	v_lshl_add_u64 v[236:237], s[46:47], 0, v[158:159]
	s_add_i32 m0, s49, 0xe000
	s_nop 0
	global_load_lds_dwordx4 v[236:237], off
	s_waitcnt vmcnt(8)
	s_waitcnt lgkmcnt(0)
	s_barrier
	s_waitcnt lgkmcnt(0)
	v_mfma_f32_16x16x32_bf16 v[128:131], v[160:163], v[204:207], v[128:131]
	v_mfma_f32_16x16x32_bf16 v[120:123], v[180:183], v[204:207], v[120:123]
	v_mfma_f32_16x16x32_bf16 v[112:115], v[160:163], v[212:215], v[112:115]
	v_mfma_f32_16x16x32_bf16 v[104:107], v[180:183], v[212:215], v[104:107]
	v_mfma_f32_16x16x32_bf16 v[96:99], v[160:163], v[220:223], v[96:99]
	v_mfma_f32_16x16x32_bf16 v[88:91], v[180:183], v[220:223], v[88:91]
	v_mfma_f32_16x16x32_bf16 v[80:83], v[160:163], v[228:231], v[80:83]
	v_mfma_f32_16x16x32_bf16 v[72:75], v[180:183], v[228:231], v[72:75]
	v_mfma_f32_16x16x32_bf16 v[128:131], v[176:179], v[208:211], v[128:131]
	v_mfma_f32_16x16x32_bf16 v[120:123], v[184:187], v[208:211], v[120:123]
	v_mfma_f32_16x16x32_bf16 v[112:115], v[176:179], v[216:219], v[112:115]
	v_mfma_f32_16x16x32_bf16 v[104:107], v[184:187], v[216:219], v[104:107]
	v_mfma_f32_16x16x32_bf16 v[96:99], v[176:179], v[224:227], v[96:99]
	v_mfma_f32_16x16x32_bf16 v[88:91], v[184:187], v[224:227], v[88:91]
	v_mfma_f32_16x16x32_bf16 v[80:83], v[176:179], v[232:235], v[80:83]
	v_mfma_f32_16x16x32_bf16 v[72:75], v[184:187], v[232:235], v[72:75]
	v_mfma_f32_16x16x32_bf16 v[124:127], v[188:191], v[204:207], v[124:127]
	v_mfma_f32_16x16x32_bf16 v[116:119], v[196:199], v[204:207], v[116:119]
	v_mfma_f32_16x16x32_bf16 v[108:111], v[188:191], v[212:215], v[108:111]
	v_mfma_f32_16x16x32_bf16 v[100:103], v[196:199], v[212:215], v[100:103]
	v_mfma_f32_16x16x32_bf16 v[92:95], v[188:191], v[220:223], v[92:95]
	v_mfma_f32_16x16x32_bf16 v[84:87], v[196:199], v[220:223], v[84:87]
	v_mfma_f32_16x16x32_bf16 v[76:79], v[188:191], v[228:231], v[76:79]
	v_mfma_f32_16x16x32_bf16 v[68:71], v[196:199], v[228:231], v[68:71]
	v_mfma_f32_16x16x32_bf16 v[124:127], v[192:195], v[208:211], v[124:127]
	v_mfma_f32_16x16x32_bf16 v[116:119], v[200:203], v[208:211], v[116:119]
	v_mfma_f32_16x16x32_bf16 v[108:111], v[192:195], v[216:219], v[108:111]
	v_mfma_f32_16x16x32_bf16 v[100:103], v[200:203], v[216:219], v[100:103]
	v_mfma_f32_16x16x32_bf16 v[92:95], v[192:195], v[224:227], v[92:95]
	v_mfma_f32_16x16x32_bf16 v[84:87], v[200:203], v[224:227], v[84:87]
	v_mfma_f32_16x16x32_bf16 v[76:79], v[192:195], v[232:235], v[76:79]
	v_mfma_f32_16x16x32_bf16 v[68:71], v[200:203], v[232:235], v[68:71]
	s_barrier
	s_add_i32 s38, s76, s48
	v_lshl_add_u64 v[236:237], s[50:51], 0, v[136:137]
	s_mov_b32 m0, s38
	ds_read_b128 v[204:207], v167 offset:16384
	ds_read_b128 v[208:211], v167 offset:17408
	ds_read_b128 v[212:215], v167 offset:18432
	ds_read_b128 v[216:219], v167 offset:19456
	ds_read_b128 v[220:223], v167 offset:20480
	ds_read_b128 v[224:227], v167 offset:21504
	ds_read_b128 v[228:231], v167 offset:22528
	ds_read_b128 v[232:235], v167 offset:23552
	global_load_lds_dwordx4 v[236:237], off
	s_add_i32 m0, s38, 0x2000
	s_add_u32 s38, s50, 0x80000
	v_lshl_add_u64 v[238:239], s[50:51], 0, v[150:151]
	s_addc_u32 s39, s51, 0
	s_add_i32 s20, s20, s48
	global_load_lds_dwordx4 v[238:239], off
	v_lshl_add_u64 v[240:241], s[38:39], 0, v[136:137]
	s_mov_b32 m0, s20
	v_lshl_add_u64 v[242:243], s[52:53], 0, v[152:153]
	global_load_lds_dwordx4 v[240:241], off
	v_lshl_add_u64 v[240:241], s[38:39], 0, v[150:151]
	s_add_i32 m0, s20, 0x2000
	s_nop 0
	global_load_lds_dwordx4 v[240:241], off
	v_lshl_add_u64 v[240:241], s[52:53], 0, v[154:155]
	s_mov_b32 m0, s49
	s_nop 0
	global_load_lds_dwordx4 v[240:241], off
	s_mov_b32 m0, s54
	s_nop 0
	global_load_lds_dwordx4 v[242:243], off
	s_waitcnt vmcnt(8)
	s_waitcnt lgkmcnt(0)
	s_barrier
; #define PG8_STAGE(bufoff, gbase, voff) do { _Pragma("unroll") for (int _i = 0; _i < 2; ++_i) \
;         __builtin_amdgcn_global_load_lds((const unsigned*)((const char*)(gbase) + (voff)[_i]), (PG8_LAS unsigned*)(lds + (bufoff) + ldsw + _i * 8192), 16, 0, 0); } while (0)
; #define PG8_LDA(dst, b, h) do { _Pragma("unroll") for (int m = 0; m < 4; ++m) _Pragma("unroll") for (int k = 0; k < 2; ++k) dst[m][k] = *(const PG8_LAS bf16x8*)(lds + PG8_SA(b, h) + aoff + m * 2048 + k * 1024); } while (0)
; #define PG8_LDB(dst, b, h) do { _Pragma("unroll") for (int n = 0; n < 2; ++n) _Pragma("unroll") for (int k = 0; k < 2; ++k) dst[n][k] = *(const PG8_LAS bf16x8*)(lds + PG8_SB(b, h) + boff + n * 2048 + k * 1024); } while (0)
; #define PG8_MMA(ai, bj, At, Bt) do { __builtin_amdgcn_s_setprio(1); _Pragma("unroll") for (int m = 0; m < 4; ++m) _Pragma("unroll") for (int n = 0; n < 2; ++n) _Pragma("unroll") for (int k = 0; k < 2; ++k) \
;         acc[ai][bj][m][n] = __builtin_amdgcn_mfma_f32_16x16x32_bf16(Bt[n][k], At[m][k], acc[ai][bj][m][n], 0, 0, 0); __builtin_amdgcn_s_setprio(0); } while (0)
; #define PG8_WAIT_V(n) asm volatile("s_waitcnt vmcnt(" #n ")" ::: "memory")
; #define PG8_WAIT_L(n) asm volatile("s_waitcnt lgkmcnt(" #n ")" ::: "memory")
; #define PG8_BAR __builtin_amdgcn_s_barrier()
; #define PG8_SCHED __builtin_amdgcn_sched_barrier(0)
; template <class Epi, class Sched, bool ALIGN_EPI = false, bool SP2 = false>
; __device__ __forceinline__ void gemm_phase(PG8_LAS unsigned char* lds, const Gemm g, const Sched& S, const Epi& E) {
;     ...
;             PG8_LDA(At, 0, 1); PG8_STAGE(PG8_SB(0, 0), b2, voffB); PG8_STAGE(PG8_SB(0, 1), b2 + hstep, voffB); PG8_STAGE(PG8_SA(0, 0), a2, voffA);
;             PG8_WAIT_V(8); PG8_WAIT_L(0); PG8_BAR; PG8_MMA(1, 0, At, B0); PG8_MMA(1, 1, At, B1); PG8_BAR; PG8_SCHED;
;             PG8_LDB(B0, 1, 0); PG8_LDB(B1, 1, 1); PG8_SCHED; PG8_LDA(At, 1, 0); PG8_STAGE(PG8_SA(0, 1), a2 + hstep, voffA);
;             PG8_WAIT_V(8); PG8_WAIT_L(0); PG8_BAR; PG8_MMA(0, 0, At, B0); PG8_MMA(0, 1, At, B1); PG8_BAR; PG8_SCHED;
	s_waitcnt lgkmcnt(0)
	v_mfma_f32_16x16x32_bf16 v[64:67], v[160:163], v[204:207], v[64:67]
	v_mfma_f32_16x16x32_bf16 v[56:59], v[180:183], v[204:207], v[56:59]
	v_mfma_f32_16x16x32_bf16 v[48:51], v[160:163], v[212:215], v[48:51]
	v_mfma_f32_16x16x32_bf16 v[40:43], v[180:183], v[212:215], v[40:43]
	v_mfma_f32_16x16x32_bf16 v[32:35], v[160:163], v[220:223], v[32:35]
	v_mfma_f32_16x16x32_bf16 v[24:27], v[180:183], v[220:223], v[24:27]
	v_mfma_f32_16x16x32_bf16 v[16:19], v[160:163], v[228:231], v[16:19]
	v_mfma_f32_16x16x32_bf16 v[8:11], v[180:183], v[228:231], v[8:11]
	v_mfma_f32_16x16x32_bf16 v[64:67], v[176:179], v[208:211], v[64:67]
	v_mfma_f32_16x16x32_bf16 v[56:59], v[184:187], v[208:211], v[56:59]
	v_mfma_f32_16x16x32_bf16 v[48:51], v[176:179], v[216:219], v[48:51]
	v_mfma_f32_16x16x32_bf16 v[40:43], v[184:187], v[216:219], v[40:43]
	v_mfma_f32_16x16x32_bf16 v[32:35], v[176:179], v[224:227], v[32:35]
	v_mfma_f32_16x16x32_bf16 v[24:27], v[184:187], v[224:227], v[24:27]
	v_mfma_f32_16x16x32_bf16 v[16:19], v[176:179], v[232:235], v[16:19]
	v_mfma_f32_16x16x32_bf16 v[8:11], v[184:187], v[232:235], v[8:11]
	v_mfma_f32_16x16x32_bf16 v[60:63], v[188:191], v[204:207], v[60:63]
	v_mfma_f32_16x16x32_bf16 v[52:55], v[196:199], v[204:207], v[52:55]
	v_mfma_f32_16x16x32_bf16 v[44:47], v[188:191], v[212:215], v[44:47]
	v_mfma_f32_16x16x32_bf16 v[36:39], v[196:199], v[212:215], v[36:39]
	v_mfma_f32_16x16x32_bf16 v[28:31], v[188:191], v[220:223], v[28:31]
	v_mfma_f32_16x16x32_bf16 v[20:23], v[196:199], v[220:223], v[20:23]
	v_mfma_f32_16x16x32_bf16 v[12:15], v[188:191], v[228:231], v[12:15]
	v_mfma_f32_16x16x32_bf16 v[4:7], v[196:199], v[228:231], v[4:7]
	v_mfma_f32_16x16x32_bf16 v[60:63], v[192:195], v[208:211], v[60:63]
	v_mfma_f32_16x16x32_bf16 v[52:55], v[200:203], v[208:211], v[52:55]
	v_mfma_f32_16x16x32_bf16 v[44:47], v[192:195], v[216:219], v[44:47]
	v_mfma_f32_16x16x32_bf16 v[36:39], v[200:203], v[216:219], v[36:39]
	v_mfma_f32_16x16x32_bf16 v[28:31], v[192:195], v[224:227], v[28:31]
	v_mfma_f32_16x16x32_bf16 v[20:23], v[200:203], v[224:227], v[20:23]
	v_mfma_f32_16x16x32_bf16 v[12:15], v[192:195], v[232:235], v[12:15]
	v_mfma_f32_16x16x32_bf16 v[4:7], v[200:203], v[232:235], v[4:7]
	s_barrier
	s_add_i32 s20, 0, 0x18000
	s_add_i32 s76, 0, 0x1c000
	v_add_u32_e32 v184, s20, v165
	v_add_u32_e32 v200, s76, v165
	ds_read_b128 v[160:163], v184
	ds_read_b128 v[176:179], v184 offset:1024
	ds_read_b128 v[180:183], v184 offset:2048
	ds_read_b128 v[184:187], v184 offset:3072
	ds_read_b128 v[188:191], v200
	ds_read_b128 v[192:195], v200 offset:1024
	ds_read_b128 v[196:199], v200 offset:2048
	ds_read_b128 v[200:203], v200 offset:3072
	s_add_u32 s38, s52, 0x80000
	s_addc_u32 s39, s53, 0
	s_mov_b32 m0, s55
	v_lshl_add_u64 v[244:245], s[38:39], 0, v[154:155]
	ds_read_b128 v[204:207], v167 offset:32768
	ds_read_b128 v[208:211], v167 offset:33792
	ds_read_b128 v[212:215], v167 offset:34816
	ds_read_b128 v[216:219], v167 offset:35840
	ds_read_b128 v[220:223], v167 offset:36864
	ds_read_b128 v[224:227], v167 offset:37888
	ds_read_b128 v[228:231], v167 offset:38912
	ds_read_b128 v[232:235], v167 offset:39936
	global_load_lds_dwordx4 v[244:245], off
	v_lshl_add_u64 v[244:245], s[38:39], 0, v[152:153]
	s_mov_b32 m0, s84
	s_nop 0
	global_load_lds_dwordx4 v[244:245], off
	s_waitcnt vmcnt(8)
	s_waitcnt lgkmcnt(0)
	s_barrier
	s_waitcnt lgkmcnt(0)
	v_mfma_f32_16x16x32_bf16 v[128:131], v[160:163], v[204:207], v[128:131]
	v_mfma_f32_16x16x32_bf16 v[120:123], v[180:183], v[204:207], v[120:123]
	v_mfma_f32_16x16x32_bf16 v[112:115], v[160:163], v[212:215], v[112:115]
	v_mfma_f32_16x16x32_bf16 v[104:107], v[180:183], v[212:215], v[104:107]
	v_mfma_f32_16x16x32_bf16 v[96:99], v[160:163], v[220:223], v[96:99]
	v_mfma_f32_16x16x32_bf16 v[88:91], v[180:183], v[220:223], v[88:91]
	v_mfma_f32_16x16x32_bf16 v[80:83], v[160:163], v[228:231], v[80:83]
	v_mfma_f32_16x16x32_bf16 v[72:75], v[180:183], v[228:231], v[72:75]
	v_mfma_f32_16x16x32_bf16 v[128:131], v[176:179], v[208:211], v[128:131]
	v_mfma_f32_16x16x32_bf16 v[120:123], v[184:187], v[208:211], v[120:123]
	v_mfma_f32_16x16x32_bf16 v[112:115], v[176:179], v[216:219], v[112:115]
	v_mfma_f32_16x16x32_bf16 v[104:107], v[184:187], v[216:219], v[104:107]
	v_mfma_f32_16x16x32_bf16 v[96:99], v[176:179], v[224:227], v[96:99]
	v_mfma_f32_16x16x32_bf16 v[88:91], v[184:187], v[224:227], v[88:91]
	v_mfma_f32_16x16x32_bf16 v[80:83], v[176:179], v[232:235], v[80:83]
	v_mfma_f32_16x16x32_bf16 v[72:75], v[184:187], v[232:235], v[72:75]
	v_mfma_f32_16x16x32_bf16 v[124:127], v[188:191], v[204:207], v[124:127]
	v_mfma_f32_16x16x32_bf16 v[116:119], v[196:199], v[204:207], v[116:119]
	v_mfma_f32_16x16x32_bf16 v[108:111], v[188:191], v[212:215], v[108:111]
	v_mfma_f32_16x16x32_bf16 v[100:103], v[196:199], v[212:215], v[100:103]
	v_mfma_f32_16x16x32_bf16 v[92:95], v[188:191], v[220:223], v[92:95]
	v_mfma_f32_16x16x32_bf16 v[84:87], v[196:199], v[220:223], v[84:87]
	v_mfma_f32_16x16x32_bf16 v[76:79], v[188:191], v[228:231], v[76:79]
	v_mfma_f32_16x16x32_bf16 v[68:71], v[196:199], v[228:231], v[68:71]
	v_mfma_f32_16x16x32_bf16 v[124:127], v[192:195], v[208:211], v[124:127]
	v_mfma_f32_16x16x32_bf16 v[116:119], v[200:203], v[208:211], v[116:119]
	v_mfma_f32_16x16x32_bf16 v[108:111], v[192:195], v[216:219], v[108:111]
	v_mfma_f32_16x16x32_bf16 v[100:103], v[200:203], v[216:219], v[100:103]
	v_mfma_f32_16x16x32_bf16 v[92:95], v[192:195], v[224:227], v[92:95]
	v_mfma_f32_16x16x32_bf16 v[84:87], v[200:203], v[224:227], v[84:87]
	v_mfma_f32_16x16x32_bf16 v[76:79], v[192:195], v[232:235], v[76:79]
	v_mfma_f32_16x16x32_bf16 v[68:71], v[200:203], v[232:235], v[68:71]
	s_barrier
; #define PG8_STAGE(bufoff, gbase, voff) do { _Pragma("unroll") for (int _i = 0; _i < 2; ++_i) \
;         __builtin_amdgcn_global_load_lds((const unsigned*)((const char*)(gbase) + (voff)[_i]), (PG8_LAS unsigned*)(lds + (bufoff) + ldsw + _i * 8192), 16, 0, 0); } while (0)
; #define PG8_LDA(dst, b, h) do { _Pragma("unroll") for (int m = 0; m < 4; ++m) _Pragma("unroll") for (int k = 0; k < 2; ++k) dst[m][k] = *(const PG8_LAS bf16x8*)(lds + PG8_SA(b, h) + aoff + m * 2048 + k * 1024); } while (0)
; #define PG8_LDB(dst, b, h) do { _Pragma("unroll") for (int n = 0; n < 2; ++n) _Pragma("unroll") for (int k = 0; k < 2; ++k) dst[n][k] = *(const PG8_LAS bf16x8*)(lds + PG8_SB(b, h) + boff + n * 2048 + k * 1024); } while (0)
; #define PG8_MMA(ai, bj, At, Bt) do { __builtin_amdgcn_s_setprio(1); _Pragma("unroll") for (int m = 0; m < 4; ++m) _Pragma("unroll") for (int n = 0; n < 2; ++n) _Pragma("unroll") for (int k = 0; k < 2; ++k) \
;         acc[ai][bj][m][n] = __builtin_amdgcn_mfma_f32_16x16x32_bf16(Bt[n][k], At[m][k], acc[ai][bj][m][n], 0, 0, 0); __builtin_amdgcn_s_setprio(0); } while (0)
; #define PG8_WAIT_V(n) asm volatile("s_waitcnt vmcnt(" #n ")" ::: "memory")
; #define PG8_WAIT_L(n) asm volatile("s_waitcnt lgkmcnt(" #n ")" ::: "memory")
; #define PG8_BAR __builtin_amdgcn_s_barrier()
; #define PG8_SCHED __builtin_amdgcn_sched_barrier(0)
; template <class Epi, class Sched, bool ALIGN_EPI = false, bool SP2 = false>
; __device__ __forceinline__ void gemm_phase(PG8_LAS unsigned char* lds, const Gemm g, const Sched& S, const Epi& E) {
;     ...
;         for (int t = 0; t < nt; t += 2) {
;     ...
;             PG8_LDB(B0, 1, 0); PG8_LDB(B1, 1, 1); PG8_SCHED; PG8_LDA(At, 1, 0); PG8_STAGE(PG8_SA(0, 1), a2 + hstep, voffA);
;             PG8_WAIT_V(8); PG8_WAIT_L(0); PG8_BAR; PG8_MMA(0, 0, At, B0); PG8_MMA(0, 1, At, B1); PG8_BAR; PG8_SCHED;
;             PG8_LDA(At, 1, 1); PG8_STAGE(PG8_SB(1, 0), b3, voffB); PG8_STAGE(PG8_SB(1, 1), b3 + hstep, voffB); PG8_STAGE(PG8_SA(1, 0), a3, voffA);
;             PG8_WAIT_V(8); PG8_WAIT_L(0); PG8_BAR; PG8_MMA(1, 0, At, B0); PG8_MMA(1, 1, At, B1); PG8_BAR; PG8_SCHED;
	s_add_i32 s20, s20, s48
	v_lshl_add_u64 v[236:237], v[236:237], 0, s[34:35]
	s_mov_b32 m0, s20
	ds_read_b128 v[204:207], v167 offset:49152
	ds_read_b128 v[208:211], v167 offset:50176
	ds_read_b128 v[212:215], v167 offset:51200
	ds_read_b128 v[216:219], v167 offset:52224
	ds_read_b128 v[220:223], v167 offset:53248
	ds_read_b128 v[224:227], v167 offset:54272
	ds_read_b128 v[228:231], v167 offset:55296
	ds_read_b128 v[232:235], v167 offset:56320
	global_load_lds_dwordx4 v[236:237], off
	s_add_i32 m0, s20, 0x2000
	s_add_u32 s38, s50, 0x80080
	v_lshl_add_u64 v[236:237], v[238:239], 0, s[34:35]
	s_addc_u32 s39, s51, 0
	s_add_i32 s20, s76, s48
	global_load_lds_dwordx4 v[236:237], off
	v_lshl_add_u64 v[236:237], s[38:39], 0, v[136:137]
	s_mov_b32 m0, s20
	s_nop 0
	global_load_lds_dwordx4 v[236:237], off
	v_lshl_add_u64 v[236:237], s[38:39], 0, v[150:151]
	s_add_i32 m0, s20, 0x2000
	s_nop 0
	global_load_lds_dwordx4 v[236:237], off
	v_lshl_add_u64 v[236:237], v[240:241], 0, s[34:35]
	s_mov_b32 m0, s85
	s_nop 0
	global_load_lds_dwordx4 v[236:237], off
	v_lshl_add_u64 v[236:237], v[242:243], 0, s[34:35]
	s_mov_b32 m0, s86
	s_nop 0
	global_load_lds_dwordx4 v[236:237], off
	s_waitcnt vmcnt(8)
	s_waitcnt lgkmcnt(0)
	s_barrier
	s_waitcnt lgkmcnt(0)
	v_mfma_f32_16x16x32_bf16 v[64:67], v[160:163], v[204:207], v[64:67]
	v_mfma_f32_16x16x32_bf16 v[56:59], v[180:183], v[204:207], v[56:59]
	v_mfma_f32_16x16x32_bf16 v[48:51], v[160:163], v[212:215], v[48:51]
	v_mfma_f32_16x16x32_bf16 v[40:43], v[180:183], v[212:215], v[40:43]
	v_mfma_f32_16x16x32_bf16 v[32:35], v[160:163], v[220:223], v[32:35]
	v_mfma_f32_16x16x32_bf16 v[24:27], v[180:183], v[220:223], v[24:27]
	v_mfma_f32_16x16x32_bf16 v[16:19], v[160:163], v[228:231], v[16:19]
	v_mfma_f32_16x16x32_bf16 v[8:11], v[180:183], v[228:231], v[8:11]
	v_mfma_f32_16x16x32_bf16 v[64:67], v[176:179], v[208:211], v[64:67]
	v_mfma_f32_16x16x32_bf16 v[56:59], v[184:187], v[208:211], v[56:59]
	v_mfma_f32_16x16x32_bf16 v[48:51], v[176:179], v[216:219], v[48:51]
	v_mfma_f32_16x16x32_bf16 v[40:43], v[184:187], v[216:219], v[40:43]
	v_mfma_f32_16x16x32_bf16 v[32:35], v[176:179], v[224:227], v[32:35]
	v_mfma_f32_16x16x32_bf16 v[24:27], v[184:187], v[224:227], v[24:27]
	v_mfma_f32_16x16x32_bf16 v[16:19], v[176:179], v[232:235], v[16:19]
	v_mfma_f32_16x16x32_bf16 v[8:11], v[184:187], v[232:235], v[8:11]
	v_mfma_f32_16x16x32_bf16 v[60:63], v[188:191], v[204:207], v[60:63]
	v_mfma_f32_16x16x32_bf16 v[52:55], v[196:199], v[204:207], v[52:55]
	v_mfma_f32_16x16x32_bf16 v[44:47], v[188:191], v[212:215], v[44:47]
	v_mfma_f32_16x16x32_bf16 v[36:39], v[196:199], v[212:215], v[36:39]
	v_mfma_f32_16x16x32_bf16 v[28:31], v[188:191], v[220:223], v[28:31]
	v_mfma_f32_16x16x32_bf16 v[20:23], v[196:199], v[220:223], v[20:23]
	v_mfma_f32_16x16x32_bf16 v[12:15], v[188:191], v[228:231], v[12:15]
	v_mfma_f32_16x16x32_bf16 v[4:7], v[196:199], v[228:231], v[4:7]
	v_mfma_f32_16x16x32_bf16 v[60:63], v[192:195], v[208:211], v[60:63]
	v_mfma_f32_16x16x32_bf16 v[52:55], v[200:203], v[208:211], v[52:55]
	v_mfma_f32_16x16x32_bf16 v[44:47], v[192:195], v[216:219], v[44:47]
	v_mfma_f32_16x16x32_bf16 v[36:39], v[200:203], v[216:219], v[36:39]
	v_mfma_f32_16x16x32_bf16 v[28:31], v[192:195], v[224:227], v[28:31]
	v_mfma_f32_16x16x32_bf16 v[20:23], v[200:203], v[224:227], v[20:23]
	v_mfma_f32_16x16x32_bf16 v[12:15], v[192:195], v[232:235], v[12:15]
	v_mfma_f32_16x16x32_bf16 v[4:7], v[200:203], v[232:235], v[4:7]
	s_barrier
	s_add_i32 s79, s79, 2
	s_add_u32 s46, s46, 0x100
	s_addc_u32 s47, s47, 0
	s_add_u32 vcc_hi, vcc_hi, 0x100
	s_addc_u32 s78, s78, 0
	s_cmp_gt_u32 s79, 29
	s_cbranch_scc0 .LBB0_151
	s_and_b64 vcc, exec, s[4:5]
	s_cbranch_vccz .LBB0_154
	s_barrier

; #define PG8_STAGE(bufoff, gbase, voff) do { _Pragma("unroll") for (int _i = 0; _i < 2; ++_i) \
;         __builtin_amdgcn_global_load_lds((const unsigned*)((const char*)(gbase) + (voff)[_i]), (PG8_LAS unsigned*)(lds + (bufoff) + ldsw + _i * 8192), 16, 0, 0); } while (0)
; #define PG8_LDA(dst, b, h) do { _Pragma("unroll") for (int m = 0; m < 4; ++m) _Pragma("unroll") for (int k = 0; k < 2; ++k) dst[m][k] = *(const PG8_LAS bf16x8*)(lds + PG8_SA(b, h) + aoff + m * 2048 + k * 1024); } while (0)
; #define PG8_LDB(dst, b, h) do { _Pragma("unroll") for (int n = 0; n < 2; ++n) _Pragma("unroll") for (int k = 0; k < 2; ++k) dst[n][k] = *(const PG8_LAS bf16x8*)(lds + PG8_SB(b, h) + boff + n * 2048 + k * 1024); } while (0)
; #define PG8_MMA(ai, bj, At, Bt) do { __builtin_amdgcn_s_setprio(1); _Pragma("unroll") for (int m = 0; m < 4; ++m) _Pragma("unroll") for (int n = 0; n < 2; ++n) _Pragma("unroll") for (int k = 0; k < 2; ++k) \
;         acc[ai][bj][m][n] = __builtin_amdgcn_mfma_f32_16x16x32_bf16(Bt[n][k], At[m][k], acc[ai][bj][m][n], 0, 0, 0); __builtin_amdgcn_s_setprio(0); } while (0)
; #define PG8_WAIT_V(n) asm volatile("s_waitcnt vmcnt(" #n ")" ::: "memory")
; #define PG8_WAIT_L(n) asm volatile("s_waitcnt lgkmcnt(" #n ")" ::: "memory")
; #define PG8_BAR __builtin_amdgcn_s_barrier()
; #define PG8_SCHED __builtin_amdgcn_sched_barrier(0)
; template <class Epi, class Sched, bool ALIGN_EPI = false, bool SP2 = false>
; __device__ __forceinline__ void gemm_phase(PG8_LAS unsigned char* lds, const Gemm g, const Sched& S, const Epi& E) {
;     ...
;             PG8_LDB(B0, 0, 0); PG8_LDB(B1, 0, 1); PG8_SCHED; PG8_LDA(At, 0, 0); PG8_STAGE(PG8_SA(1, 1), a1 + hstep, voffA);
;             PG8_WAIT_V(8); PG8_WAIT_L(0); PG8_BAR; PG8_MMA(0, 0, At, B0); PG8_MMA(0, 1, At, B1); PG8_BAR; PG8_SCHED;
;             PG8_LDA(At, 0, 1); PG8_STAGE(PG8_SB(0, 0), b2, voffB); PG8_STAGE(PG8_SB(0, 1), b2 + hstep, voffB); PG8_STAGE(PG8_SA(0, 0), a2, voffA);
;             PG8_WAIT_V(8); PG8_WAIT_L(0); PG8_BAR; PG8_MMA(1, 0, At, B0); PG8_MMA(1, 1, At, B1); PG8_BAR; PG8_SCHED;
.LBB0_228:
	s_add_u32 s42, s30, 0x100
	s_addc_u32 s43, s31, 0
	s_add_i32 s38, 0, 0x10000
	s_cmpk_eq_i32 s97, 0x54
	s_cselect_b32 s51, s25, s43
	s_cselect_b32 s50, s24, s42
	s_cselect_b32 s47, s27, s79
	s_cselect_b32 s46, s26, s78
	s_add_i32 s39, 0, 0x14000
	v_add_u32_e32 v184, s38, v177
	v_add_u32_e32 v200, s39, v177
	ds_read_b128 v[160:163], v184
	ds_read_b128 v[164:167], v184 offset:1024
	ds_read_b128 v[180:183], v184 offset:2048
	ds_read_b128 v[184:187], v184 offset:3072
	ds_read_b128 v[188:191], v200
	ds_read_b128 v[192:195], v200 offset:1024
	ds_read_b128 v[196:199], v200 offset:2048
	ds_read_b128 v[200:203], v200 offset:3072
	v_lshl_add_u64 v[236:237], s[30:31], 0, v[156:157]
	s_add_i32 m0, s55, 0xc000
	ds_read_b128 v[204:207], v179
	ds_read_b128 v[208:211], v179 offset:1024
	ds_read_b128 v[212:215], v179 offset:2048
	ds_read_b128 v[216:219], v179 offset:3072
	ds_read_b128 v[220:223], v179 offset:4096
	ds_read_b128 v[224:227], v179 offset:5120
	ds_read_b128 v[228:231], v179 offset:6144
	ds_read_b128 v[232:235], v179 offset:7168
	global_load_lds_dwordx4 v[236:237], off
	v_lshl_add_u64 v[236:237], s[30:31], 0, v[158:159]
	s_add_i32 m0, s55, 0xe000
	s_nop 0
	global_load_lds_dwordx4 v[236:237], off
	s_waitcnt vmcnt(8)
	s_waitcnt lgkmcnt(0)
	s_barrier
	s_waitcnt lgkmcnt(0)
	v_mfma_f32_16x16x32_bf16 v[128:131], v[160:163], v[204:207], v[128:131]
	v_mfma_f32_16x16x32_bf16 v[124:127], v[180:183], v[204:207], v[124:127]
	v_mfma_f32_16x16x32_bf16 v[120:123], v[160:163], v[212:215], v[120:123]
	v_mfma_f32_16x16x32_bf16 v[116:119], v[180:183], v[212:215], v[116:119]
	v_mfma_f32_16x16x32_bf16 v[96:99], v[160:163], v[220:223], v[96:99]
	v_mfma_f32_16x16x32_bf16 v[92:95], v[180:183], v[220:223], v[92:95]
	v_mfma_f32_16x16x32_bf16 v[88:91], v[160:163], v[228:231], v[88:91]
	v_mfma_f32_16x16x32_bf16 v[84:87], v[180:183], v[228:231], v[84:87]
	v_mfma_f32_16x16x32_bf16 v[128:131], v[164:167], v[208:211], v[128:131]
	v_mfma_f32_16x16x32_bf16 v[124:127], v[184:187], v[208:211], v[124:127]
	v_mfma_f32_16x16x32_bf16 v[120:123], v[164:167], v[216:219], v[120:123]
	v_mfma_f32_16x16x32_bf16 v[116:119], v[184:187], v[216:219], v[116:119]
	v_mfma_f32_16x16x32_bf16 v[96:99], v[164:167], v[224:227], v[96:99]
	v_mfma_f32_16x16x32_bf16 v[92:95], v[184:187], v[224:227], v[92:95]
	v_mfma_f32_16x16x32_bf16 v[88:91], v[164:167], v[232:235], v[88:91]
	v_mfma_f32_16x16x32_bf16 v[84:87], v[184:187], v[232:235], v[84:87]
	v_mfma_f32_16x16x32_bf16 v[112:115], v[188:191], v[204:207], v[112:115]
	v_mfma_f32_16x16x32_bf16 v[108:111], v[196:199], v[204:207], v[108:111]
	v_mfma_f32_16x16x32_bf16 v[104:107], v[188:191], v[212:215], v[104:107]
	v_mfma_f32_16x16x32_bf16 v[100:103], v[196:199], v[212:215], v[100:103]
	v_mfma_f32_16x16x32_bf16 v[80:83], v[188:191], v[220:223], v[80:83]
	v_mfma_f32_16x16x32_bf16 v[76:79], v[196:199], v[220:223], v[76:79]
	v_mfma_f32_16x16x32_bf16 v[72:75], v[188:191], v[228:231], v[72:75]
	v_mfma_f32_16x16x32_bf16 v[68:71], v[196:199], v[228:231], v[68:71]
	v_mfma_f32_16x16x32_bf16 v[112:115], v[192:195], v[208:211], v[112:115]
	v_mfma_f32_16x16x32_bf16 v[108:111], v[200:203], v[208:211], v[108:111]
	v_mfma_f32_16x16x32_bf16 v[104:107], v[192:195], v[216:219], v[104:107]
	v_mfma_f32_16x16x32_bf16 v[100:103], v[200:203], v[216:219], v[100:103]
	v_mfma_f32_16x16x32_bf16 v[80:83], v[192:195], v[224:227], v[80:83]
	v_mfma_f32_16x16x32_bf16 v[76:79], v[200:203], v[224:227], v[76:79]
	v_mfma_f32_16x16x32_bf16 v[72:75], v[192:195], v[232:235], v[72:75]
	v_mfma_f32_16x16x32_bf16 v[68:71], v[200:203], v[232:235], v[68:71]
	s_barrier
	s_add_i32 s30, s38, s54
	v_lshl_add_u64 v[236:237], s[46:47], 0, v[136:137]
	s_mov_b32 m0, s30
	ds_read_b128 v[204:207], v179 offset:16384
	ds_read_b128 v[208:211], v179 offset:17408
	ds_read_b128 v[212:215], v179 offset:18432
	ds_read_b128 v[216:219], v179 offset:19456
	ds_read_b128 v[220:223], v179 offset:20480
	ds_read_b128 v[224:227], v179 offset:21504
	ds_read_b128 v[228:231], v179 offset:22528
	ds_read_b128 v[232:235], v179 offset:23552
	global_load_lds_dwordx4 v[236:237], off
	s_add_i32 m0, s30, 0x2000
	s_add_u32 s30, s46, 0x160000
	v_lshl_add_u64 v[238:239], s[46:47], 0, v[150:151]
	s_addc_u32 s31, s47, 0
	s_add_i32 s38, s39, s54
	global_load_lds_dwordx4 v[238:239], off
	v_lshl_add_u64 v[240:241], s[30:31], 0, v[136:137]
	s_mov_b32 m0, s38
	v_lshl_add_u64 v[242:243], s[50:51], 0, v[152:153]
	global_load_lds_dwordx4 v[240:241], off
	v_lshl_add_u64 v[240:241], s[30:31], 0, v[150:151]
	s_add_i32 m0, s38, 0x2000
	s_nop 0
	global_load_lds_dwordx4 v[240:241], off
	v_lshl_add_u64 v[240:241], s[50:51], 0, v[154:155]
	s_mov_b32 m0, s55
	s_nop 0
	global_load_lds_dwordx4 v[240:241], off
	s_mov_b32 m0, s86
	s_nop 0
	global_load_lds_dwordx4 v[242:243], off
	s_waitcnt vmcnt(8)
	s_waitcnt lgkmcnt(0)
	s_barrier
; #define PG8_STAGE(bufoff, gbase, voff) do { _Pragma("unroll") for (int _i = 0; _i < 2; ++_i) \
;         __builtin_amdgcn_global_load_lds((const unsigned*)((const char*)(gbase) + (voff)[_i]), (PG8_LAS unsigned*)(lds + (bufoff) + ldsw + _i * 8192), 16, 0, 0); } while (0)
; #define PG8_LDA(dst, b, h) do { _Pragma("unroll") for (int m = 0; m < 4; ++m) _Pragma("unroll") for (int k = 0; k < 2; ++k) dst[m][k] = *(const PG8_LAS bf16x8*)(lds + PG8_SA(b, h) + aoff + m * 2048 + k * 1024); } while (0)
; #define PG8_LDB(dst, b, h) do { _Pragma("unroll") for (int n = 0; n < 2; ++n) _Pragma("unroll") for (int k = 0; k < 2; ++k) dst[n][k] = *(const PG8_LAS bf16x8*)(lds + PG8_SB(b, h) + boff + n * 2048 + k * 1024); } while (0)
; #define PG8_MMA(ai, bj, At, Bt) do { __builtin_amdgcn_s_setprio(1); _Pragma("unroll") for (int m = 0; m < 4; ++m) _Pragma("unroll") for (int n = 0; n < 2; ++n) _Pragma("unroll") for (int k = 0; k < 2; ++k) \
;         acc[ai][bj][m][n] = __builtin_amdgcn_mfma_f32_16x16x32_bf16(Bt[n][k], At[m][k], acc[ai][bj][m][n], 0, 0, 0); __builtin_amdgcn_s_setprio(0); } while (0)
; #define PG8_WAIT_V(n) asm volatile("s_waitcnt vmcnt(" #n ")" ::: "memory")
; #define PG8_WAIT_L(n) asm volatile("s_waitcnt lgkmcnt(" #n ")" ::: "memory")
; #define PG8_BAR __builtin_amdgcn_s_barrier()
; #define PG8_SCHED __builtin_amdgcn_sched_barrier(0)
; template <class Epi, class Sched, bool ALIGN_EPI = false, bool SP2 = false>
; __device__ __forceinline__ void gemm_phase(PG8_LAS unsigned char* lds, const Gemm g, const Sched& S, const Epi& E) {
;     ...
;             PG8_WAIT_V(8); PG8_WAIT_L(0); PG8_BAR; PG8_MMA(1, 0, At, B0); PG8_MMA(1, 1, At, B1); PG8_BAR; PG8_SCHED;
;             PG8_LDB(B0, 1, 0); PG8_LDB(B1, 1, 1); PG8_SCHED; PG8_LDA(At, 1, 0); PG8_STAGE(PG8_SA(0, 1), a2 + hstep, voffA);
;             PG8_WAIT_V(8); PG8_WAIT_L(0); PG8_BAR; PG8_MMA(0, 0, At, B0); PG8_MMA(0, 1, At, B1); PG8_BAR; PG8_SCHED;
	s_waitcnt lgkmcnt(0)
	v_mfma_f32_16x16x32_bf16 v[64:67], v[160:163], v[204:207], v[64:67]
	v_mfma_f32_16x16x32_bf16 v[60:63], v[180:183], v[204:207], v[60:63]
	v_mfma_f32_16x16x32_bf16 v[56:59], v[160:163], v[212:215], v[56:59]
	v_mfma_f32_16x16x32_bf16 v[52:55], v[180:183], v[212:215], v[52:55]
	v_mfma_f32_16x16x32_bf16 v[32:35], v[160:163], v[220:223], v[32:35]
	v_mfma_f32_16x16x32_bf16 v[28:31], v[180:183], v[220:223], v[28:31]
	v_mfma_f32_16x16x32_bf16 v[24:27], v[160:163], v[228:231], v[24:27]
	v_mfma_f32_16x16x32_bf16 v[20:23], v[180:183], v[228:231], v[20:23]
	v_mfma_f32_16x16x32_bf16 v[64:67], v[164:167], v[208:211], v[64:67]
	v_mfma_f32_16x16x32_bf16 v[60:63], v[184:187], v[208:211], v[60:63]
	v_mfma_f32_16x16x32_bf16 v[56:59], v[164:167], v[216:219], v[56:59]
	v_mfma_f32_16x16x32_bf16 v[52:55], v[184:187], v[216:219], v[52:55]
	v_mfma_f32_16x16x32_bf16 v[32:35], v[164:167], v[224:227], v[32:35]
	v_mfma_f32_16x16x32_bf16 v[28:31], v[184:187], v[224:227], v[28:31]
	v_mfma_f32_16x16x32_bf16 v[24:27], v[164:167], v[232:235], v[24:27]
	v_mfma_f32_16x16x32_bf16 v[20:23], v[184:187], v[232:235], v[20:23]
	v_mfma_f32_16x16x32_bf16 v[48:51], v[188:191], v[204:207], v[48:51]
	v_mfma_f32_16x16x32_bf16 v[44:47], v[196:199], v[204:207], v[44:47]
	v_mfma_f32_16x16x32_bf16 v[40:43], v[188:191], v[212:215], v[40:43]
	v_mfma_f32_16x16x32_bf16 v[36:39], v[196:199], v[212:215], v[36:39]
	v_mfma_f32_16x16x32_bf16 v[16:19], v[188:191], v[220:223], v[16:19]
	v_mfma_f32_16x16x32_bf16 v[12:15], v[196:199], v[220:223], v[12:15]
	v_mfma_f32_16x16x32_bf16 v[8:11], v[188:191], v[228:231], v[8:11]
	v_mfma_f32_16x16x32_bf16 v[4:7], v[196:199], v[228:231], v[4:7]
	v_mfma_f32_16x16x32_bf16 v[48:51], v[192:195], v[208:211], v[48:51]
	v_mfma_f32_16x16x32_bf16 v[44:47], v[200:203], v[208:211], v[44:47]
	v_mfma_f32_16x16x32_bf16 v[40:43], v[192:195], v[216:219], v[40:43]
	v_mfma_f32_16x16x32_bf16 v[36:39], v[200:203], v[216:219], v[36:39]
	v_mfma_f32_16x16x32_bf16 v[16:19], v[192:195], v[224:227], v[16:19]
	v_mfma_f32_16x16x32_bf16 v[12:15], v[200:203], v[224:227], v[12:15]
	v_mfma_f32_16x16x32_bf16 v[8:11], v[192:195], v[232:235], v[8:11]
	v_mfma_f32_16x16x32_bf16 v[4:7], v[200:203], v[232:235], v[4:7]
	s_barrier
	s_add_i32 s38, 0, 0x18000
	s_add_i32 s39, 0, 0x1c000
	v_add_u32_e32 v184, s38, v177
	v_add_u32_e32 v200, s39, v177
	ds_read_b128 v[160:163], v184
	ds_read_b128 v[164:167], v184 offset:1024
	ds_read_b128 v[180:183], v184 offset:2048
	ds_read_b128 v[184:187], v184 offset:3072
	ds_read_b128 v[188:191], v200
	ds_read_b128 v[192:195], v200 offset:1024
	ds_read_b128 v[196:199], v200 offset:2048
	ds_read_b128 v[200:203], v200 offset:3072
	s_add_u32 s30, s50, 0x160000
	s_addc_u32 s31, s51, 0
	s_mov_b32 m0, s88
	v_lshl_add_u64 v[244:245], s[30:31], 0, v[154:155]
	ds_read_b128 v[204:207], v179 offset:32768
	ds_read_b128 v[208:211], v179 offset:33792
	ds_read_b128 v[212:215], v179 offset:34816
	ds_read_b128 v[216:219], v179 offset:35840
	ds_read_b128 v[220:223], v179 offset:36864
	ds_read_b128 v[224:227], v179 offset:37888
	ds_read_b128 v[228:231], v179 offset:38912
	ds_read_b128 v[232:235], v179 offset:39936
	global_load_lds_dwordx4 v[244:245], off
	v_lshl_add_u64 v[244:245], s[30:31], 0, v[152:153]
	s_mov_b32 m0, s89
	s_nop 0
	global_load_lds_dwordx4 v[244:245], off
	s_waitcnt vmcnt(8)
	s_waitcnt lgkmcnt(0)
	s_barrier
	s_waitcnt lgkmcnt(0)
	v_mfma_f32_16x16x32_bf16 v[128:131], v[160:163], v[204:207], v[128:131]
	v_mfma_f32_16x16x32_bf16 v[124:127], v[180:183], v[204:207], v[124:127]
	v_mfma_f32_16x16x32_bf16 v[120:123], v[160:163], v[212:215], v[120:123]
	v_mfma_f32_16x16x32_bf16 v[116:119], v[180:183], v[212:215], v[116:119]
	v_mfma_f32_16x16x32_bf16 v[96:99], v[160:163], v[220:223], v[96:99]
	v_mfma_f32_16x16x32_bf16 v[92:95], v[180:183], v[220:223], v[92:95]
	v_mfma_f32_16x16x32_bf16 v[88:91], v[160:163], v[228:231], v[88:91]
	v_mfma_f32_16x16x32_bf16 v[84:87], v[180:183], v[228:231], v[84:87]
	v_mfma_f32_16x16x32_bf16 v[128:131], v[164:167], v[208:211], v[128:131]
	v_mfma_f32_16x16x32_bf16 v[124:127], v[184:187], v[208:211], v[124:127]
	v_mfma_f32_16x16x32_bf16 v[120:123], v[164:167], v[216:219], v[120:123]
	v_mfma_f32_16x16x32_bf16 v[116:119], v[184:187], v[216:219], v[116:119]
	v_mfma_f32_16x16x32_bf16 v[96:99], v[164:167], v[224:227], v[96:99]
	v_mfma_f32_16x16x32_bf16 v[92:95], v[184:187], v[224:227], v[92:95]
	v_mfma_f32_16x16x32_bf16 v[88:91], v[164:167], v[232:235], v[88:91]
	v_mfma_f32_16x16x32_bf16 v[84:87], v[184:187], v[232:235], v[84:87]
	v_mfma_f32_16x16x32_bf16 v[112:115], v[188:191], v[204:207], v[112:115]
	v_mfma_f32_16x16x32_bf16 v[108:111], v[196:199], v[204:207], v[108:111]
	v_mfma_f32_16x16x32_bf16 v[104:107], v[188:191], v[212:215], v[104:107]
	v_mfma_f32_16x16x32_bf16 v[100:103], v[196:199], v[212:215], v[100:103]
	v_mfma_f32_16x16x32_bf16 v[80:83], v[188:191], v[220:223], v[80:83]
	v_mfma_f32_16x16x32_bf16 v[76:79], v[196:199], v[220:223], v[76:79]
	v_mfma_f32_16x16x32_bf16 v[72:75], v[188:191], v[228:231], v[72:75]
	v_mfma_f32_16x16x32_bf16 v[68:71], v[196:199], v[228:231], v[68:71]
	v_mfma_f32_16x16x32_bf16 v[112:115], v[192:195], v[208:211], v[112:115]
	v_mfma_f32_16x16x32_bf16 v[108:111], v[200:203], v[208:211], v[108:111]
	v_mfma_f32_16x16x32_bf16 v[104:107], v[192:195], v[216:219], v[104:107]
	v_mfma_f32_16x16x32_bf16 v[100:103], v[200:203], v[216:219], v[100:103]
	v_mfma_f32_16x16x32_bf16 v[80:83], v[192:195], v[224:227], v[80:83]
	v_mfma_f32_16x16x32_bf16 v[76:79], v[200:203], v[224:227], v[76:79]
	v_mfma_f32_16x16x32_bf16 v[72:75], v[192:195], v[232:235], v[72:75]
	v_mfma_f32_16x16x32_bf16 v[68:71], v[200:203], v[232:235], v[68:71]
	s_barrier
; #define PG8_STAGE(bufoff, gbase, voff) do { _Pragma("unroll") for (int _i = 0; _i < 2; ++_i) \
;         __builtin_amdgcn_global_load_lds((const unsigned*)((const char*)(gbase) + (voff)[_i]), (PG8_LAS unsigned*)(lds + (bufoff) + ldsw + _i * 8192), 16, 0, 0); } while (0)
; #define PG8_LDA(dst, b, h) do { _Pragma("unroll") for (int m = 0; m < 4; ++m) _Pragma("unroll") for (int k = 0; k < 2; ++k) dst[m][k] = *(const PG8_LAS bf16x8*)(lds + PG8_SA(b, h) + aoff + m * 2048 + k * 1024); } while (0)
; #define PG8_MMA(ai, bj, At, Bt) do { __builtin_amdgcn_s_setprio(1); _Pragma("unroll") for (int m = 0; m < 4; ++m) _Pragma("unroll") for (int n = 0; n < 2; ++n) _Pragma("unroll") for (int k = 0; k < 2; ++k) \
;         acc[ai][bj][m][n] = __builtin_amdgcn_mfma_f32_16x16x32_bf16(Bt[n][k], At[m][k], acc[ai][bj][m][n], 0, 0, 0); __builtin_amdgcn_s_setprio(0); } while (0)
; #define PG8_WAIT_V(n) asm volatile("s_waitcnt vmcnt(" #n ")" ::: "memory")
; #define PG8_WAIT_L(n) asm volatile("s_waitcnt lgkmcnt(" #n ")" ::: "memory")
; #define PG8_BAR __builtin_amdgcn_s_barrier()
; #define PG8_SCHED __builtin_amdgcn_sched_barrier(0)
; template <class Epi, class Sched, bool ALIGN_EPI = false, bool SP2 = false>
; __device__ __forceinline__ void gemm_phase(PG8_LAS unsigned char* lds, const Gemm g, const Sched& S, const Epi& E) {
;     ...
;         for (int t = 0; t < nt; t += 2) {
;             const bool last = (t == nt - 2);
;     ...
;             PG8_LDA(At, 1, 1); PG8_STAGE(PG8_SB(1, 0), b3, voffB); PG8_STAGE(PG8_SB(1, 1), b3 + hstep, voffB); PG8_STAGE(PG8_SA(1, 0), a3, voffA);
;             PG8_WAIT_V(8); PG8_WAIT_L(0); PG8_BAR; PG8_MMA(1, 0, At, B0); PG8_MMA(1, 1, At, B1); PG8_BAR; PG8_SCHED;
	s_add_i32 s30, s38, s54
	v_lshl_add_u64 v[236:237], v[236:237], 0, s[34:35]
	s_mov_b32 m0, s30
	ds_read_b128 v[204:207], v179 offset:49152
	ds_read_b128 v[208:211], v179 offset:50176
	ds_read_b128 v[212:215], v179 offset:51200
	ds_read_b128 v[216:219], v179 offset:52224
	ds_read_b128 v[220:223], v179 offset:53248
	ds_read_b128 v[224:227], v179 offset:54272
	ds_read_b128 v[228:231], v179 offset:55296
	ds_read_b128 v[232:235], v179 offset:56320
	global_load_lds_dwordx4 v[236:237], off
	s_add_i32 m0, s30, 0x2000
	s_add_u32 s30, s46, 0x160080
	v_lshl_add_u64 v[236:237], v[238:239], 0, s[34:35]
	s_addc_u32 s31, s47, 0
	s_add_i32 s38, s39, s54
	global_load_lds_dwordx4 v[236:237], off
	v_lshl_add_u64 v[236:237], s[30:31], 0, v[136:137]
	s_mov_b32 m0, s38
	s_nop 0
	global_load_lds_dwordx4 v[236:237], off
	v_lshl_add_u64 v[236:237], s[30:31], 0, v[150:151]
	s_add_i32 m0, s38, 0x2000
	s_nop 0
	global_load_lds_dwordx4 v[236:237], off
	v_lshl_add_u64 v[236:237], v[240:241], 0, s[34:35]
	s_mov_b32 m0, s28
	s_nop 0
	global_load_lds_dwordx4 v[236:237], off
	v_lshl_add_u64 v[236:237], v[242:243], 0, s[34:35]
	s_mov_b32 m0, s29
	s_nop 0
	global_load_lds_dwordx4 v[236:237], off
	s_waitcnt vmcnt(8)
	s_waitcnt lgkmcnt(0)
	s_barrier
	s_waitcnt lgkmcnt(0)
	v_mfma_f32_16x16x32_bf16 v[64:67], v[160:163], v[204:207], v[64:67]
	v_mfma_f32_16x16x32_bf16 v[60:63], v[180:183], v[204:207], v[60:63]
	v_mfma_f32_16x16x32_bf16 v[56:59], v[160:163], v[212:215], v[56:59]
	v_mfma_f32_16x16x32_bf16 v[52:55], v[180:183], v[212:215], v[52:55]
	v_mfma_f32_16x16x32_bf16 v[32:35], v[160:163], v[220:223], v[32:35]
	v_mfma_f32_16x16x32_bf16 v[28:31], v[180:183], v[220:223], v[28:31]
	v_mfma_f32_16x16x32_bf16 v[24:27], v[160:163], v[228:231], v[24:27]
	v_mfma_f32_16x16x32_bf16 v[20:23], v[180:183], v[228:231], v[20:23]
	v_mfma_f32_16x16x32_bf16 v[64:67], v[164:167], v[208:211], v[64:67]
	v_mfma_f32_16x16x32_bf16 v[60:63], v[184:187], v[208:211], v[60:63]
	v_mfma_f32_16x16x32_bf16 v[56:59], v[164:167], v[216:219], v[56:59]
	v_mfma_f32_16x16x32_bf16 v[52:55], v[184:187], v[216:219], v[52:55]
	v_mfma_f32_16x16x32_bf16 v[32:35], v[164:167], v[224:227], v[32:35]
	v_mfma_f32_16x16x32_bf16 v[28:31], v[184:187], v[224:227], v[28:31]
	v_mfma_f32_16x16x32_bf16 v[24:27], v[164:167], v[232:235], v[24:27]
	v_mfma_f32_16x16x32_bf16 v[20:23], v[184:187], v[232:235], v[20:23]
	v_mfma_f32_16x16x32_bf16 v[48:51], v[188:191], v[204:207], v[48:51]
	v_mfma_f32_16x16x32_bf16 v[44:47], v[196:199], v[204:207], v[44:47]
	v_mfma_f32_16x16x32_bf16 v[40:43], v[188:191], v[212:215], v[40:43]
	v_mfma_f32_16x16x32_bf16 v[36:39], v[196:199], v[212:215], v[36:39]
	v_mfma_f32_16x16x32_bf16 v[16:19], v[188:191], v[220:223], v[16:19]
	v_mfma_f32_16x16x32_bf16 v[12:15], v[196:199], v[220:223], v[12:15]
	v_mfma_f32_16x16x32_bf16 v[8:11], v[188:191], v[228:231], v[8:11]
	v_mfma_f32_16x16x32_bf16 v[4:7], v[196:199], v[228:231], v[4:7]
	v_mfma_f32_16x16x32_bf16 v[48:51], v[192:195], v[208:211], v[48:51]
	v_mfma_f32_16x16x32_bf16 v[44:47], v[200:203], v[208:211], v[44:47]
	v_mfma_f32_16x16x32_bf16 v[40:43], v[192:195], v[216:219], v[40:43]
	v_mfma_f32_16x16x32_bf16 v[36:39], v[200:203], v[216:219], v[36:39]
	v_mfma_f32_16x16x32_bf16 v[16:19], v[192:195], v[224:227], v[16:19]
	v_mfma_f32_16x16x32_bf16 v[12:15], v[200:203], v[224:227], v[12:15]
	v_mfma_f32_16x16x32_bf16 v[8:11], v[192:195], v[232:235], v[8:11]
	v_mfma_f32_16x16x32_bf16 v[4:7], v[200:203], v[232:235], v[4:7]
	s_barrier
	s_add_i32 s97, s97, 2
	s_add_u32 s78, s78, 0x100
	s_addc_u32 s79, s79, 0
	s_cmpk_gt_u32 s97, 0x55
	s_mov_b64 s[30:31], s[42:43]
	s_cbranch_scc0 .LBB0_228
	s_and_b64 vcc, exec, s[4:5]
	s_cbranch_vccz .LBB0_231
	s_barrier

; #define PG8_STAGE(bufoff, gbase, voff) do { _Pragma("unroll") for (int _i = 0; _i < 2; ++_i) \
;         __builtin_amdgcn_global_load_lds((const unsigned*)((const char*)(gbase) + (voff)[_i]), (PG8_LAS unsigned*)(lds + (bufoff) + ldsw + _i * 8192), 16, 0, 0); } while (0)
; #define PG8_LDA(dst, b, h) do { _Pragma("unroll") for (int m = 0; m < 4; ++m) _Pragma("unroll") for (int k = 0; k < 2; ++k) dst[m][k] = *(const PG8_LAS bf16x8*)(lds + PG8_SA(b, h) + aoff + m * 2048 + k * 1024); } while (0)
; #define PG8_LDB(dst, b, h) do { _Pragma("unroll") for (int n = 0; n < 2; ++n) _Pragma("unroll") for (int k = 0; k < 2; ++k) dst[n][k] = *(const PG8_LAS bf16x8*)(lds + PG8_SB(b, h) + boff + n * 2048 + k * 1024); } while (0)
; #define PG8_WAIT_V(n) asm volatile("s_waitcnt vmcnt(" #n ")" ::: "memory")
; #define PG8_WAIT_L(n) asm volatile("s_waitcnt lgkmcnt(" #n ")" ::: "memory")
; #define PG8_BAR __builtin_amdgcn_s_barrier()
; #define PG8_SCHED __builtin_amdgcn_sched_barrier(0)
; template <class Epi, class Sched, bool ALIGN_EPI = false, bool SP2 = false>
; __device__ __forceinline__ void gemm_phase(PG8_LAS unsigned char* lds, const Gemm g, const Sched& S, const Epi& E) {
;     ...
;         for (int t = 0; t < nt; t += 2) {
;             const bool last = (t == nt - 2);
;             const char* a1 = cA + (size_t)(t + 1) * kstep;
;             const char* a2 = last ? nA : cA + (size_t)(t + 2) * kstep; const char* b2 = last ? nB : cB + (size_t)(t + 2) * kstep;
;             const char* a3 = a2 + kstep; const char* b3 = b2 + kstep;
;             if (last && has_next) S.a_ready(nxt);
;             if (last) E.prefetch(cur, wid, lane, lds + STAGE_BYTES + 1024);
;             if constexpr (SP2) {
;             PG8_LDB(B0, 0, 0); PG8_LDB(B1, 0, 1); PG8_SCHED; PG8_LDA(At, 0, 0); PG8_STAGE(PG8_SA(1, 1), a1 + hstep, voffA);
;             PG8_WAIT_V(8); PG8_WAIT_L(0); PG8_BAR; PG8_MMA(0, 0, At, B0); PG8_MMA(0, 1, At, B1); PG8_BAR; PG8_SCHED;
;             PG8_LDA(At, 0, 1); PG8_STAGE(PG8_SB(0, 0), b2, voffB); PG8_STAGE(PG8_SB(0, 1), b2 + hstep, voffB); PG8_STAGE(PG8_SA(0, 0), a2, voffA);
;             PG8_WAIT_V(8); PG8_WAIT_L(0); PG8_BAR; PG8_MMA(1, 0, At, B0); PG8_MMA(1, 1, At, B1); PG8_BAR; PG8_SCHED;
;             PG8_LDB(B0, 1, 0); PG8_LDB(B1, 1, 1); PG8_SCHED; PG8_LDA(At, 1, 0); PG8_STAGE(PG8_SA(0, 1), a2 + hstep, voffA);
.LBB0_352:
	s_add_u32 s20, s46, 0xfff80080
	s_addc_u32 s38, s47, -1
	s_add_i32 s39, 0, 0x10000
	s_cmp_eq_u32 s79, 28
	s_cselect_b32 s51, s27, s38
	s_cselect_b32 s50, s89, s20
	s_cselect_b32 s49, s25, s78
	s_cselect_b32 s48, s96, s97
	s_add_i32 s20, 0, 0x14000
	v_add_u32_e32 v184, s39, v165
	v_add_u32_e32 v200, s20, v165
	ds_read_b128 v[160:163], v184
	ds_read_b128 v[176:179], v184 offset:1024
	ds_read_b128 v[180:183], v184 offset:2048
	ds_read_b128 v[184:187], v184 offset:3072
	ds_read_b128 v[188:191], v200
	ds_read_b128 v[192:195], v200 offset:1024
	ds_read_b128 v[196:199], v200 offset:2048
	ds_read_b128 v[200:203], v200 offset:3072
	v_lshl_add_u64 v[236:237], s[46:47], 0, v[156:157]
	s_add_i32 m0, s29, 0xc000
	ds_read_b128 v[204:207], v167
	ds_read_b128 v[208:211], v167 offset:1024
	ds_read_b128 v[212:215], v167 offset:2048
	ds_read_b128 v[216:219], v167 offset:3072
	ds_read_b128 v[220:223], v167 offset:4096
	ds_read_b128 v[224:227], v167 offset:5120
	ds_read_b128 v[228:231], v167 offset:6144
	ds_read_b128 v[232:235], v167 offset:7168
	global_load_lds_dwordx4 v[236:237], off
	v_lshl_add_u64 v[236:237], s[46:47], 0, v[158:159]
	s_add_i32 m0, s29, 0xe000
	s_nop 0
	global_load_lds_dwordx4 v[236:237], off
	s_waitcnt vmcnt(8)
	s_waitcnt lgkmcnt(0)
	s_barrier
	s_waitcnt lgkmcnt(0)
	v_mfma_f32_16x16x32_bf16 v[128:131], v[160:163], v[204:207], v[128:131]
	v_mfma_f32_16x16x32_bf16 v[124:127], v[180:183], v[204:207], v[124:127]
	v_mfma_f32_16x16x32_bf16 v[120:123], v[160:163], v[212:215], v[120:123]
	v_mfma_f32_16x16x32_bf16 v[112:115], v[180:183], v[212:215], v[112:115]
	v_mfma_f32_16x16x32_bf16 v[104:107], v[160:163], v[220:223], v[104:107]
	v_mfma_f32_16x16x32_bf16 v[96:99], v[180:183], v[220:223], v[96:99]
	v_mfma_f32_16x16x32_bf16 v[88:91], v[160:163], v[228:231], v[88:91]
	v_mfma_f32_16x16x32_bf16 v[80:83], v[180:183], v[228:231], v[80:83]
	v_mfma_f32_16x16x32_bf16 v[128:131], v[176:179], v[208:211], v[128:131]
	v_mfma_f32_16x16x32_bf16 v[124:127], v[184:187], v[208:211], v[124:127]
	v_mfma_f32_16x16x32_bf16 v[120:123], v[176:179], v[216:219], v[120:123]
	v_mfma_f32_16x16x32_bf16 v[112:115], v[184:187], v[216:219], v[112:115]
	v_mfma_f32_16x16x32_bf16 v[104:107], v[176:179], v[224:227], v[104:107]
	v_mfma_f32_16x16x32_bf16 v[96:99], v[184:187], v[224:227], v[96:99]
	v_mfma_f32_16x16x32_bf16 v[88:91], v[176:179], v[232:235], v[88:91]
	v_mfma_f32_16x16x32_bf16 v[80:83], v[184:187], v[232:235], v[80:83]
	v_mfma_f32_16x16x32_bf16 v[116:119], v[188:191], v[204:207], v[116:119]
	v_mfma_f32_16x16x32_bf16 v[108:111], v[196:199], v[204:207], v[108:111]
	v_mfma_f32_16x16x32_bf16 v[100:103], v[188:191], v[212:215], v[100:103]
	v_mfma_f32_16x16x32_bf16 v[92:95], v[196:199], v[212:215], v[92:95]
	v_mfma_f32_16x16x32_bf16 v[84:87], v[188:191], v[220:223], v[84:87]
	v_mfma_f32_16x16x32_bf16 v[76:79], v[196:199], v[220:223], v[76:79]
	v_mfma_f32_16x16x32_bf16 v[72:75], v[188:191], v[228:231], v[72:75]
	v_mfma_f32_16x16x32_bf16 v[68:71], v[196:199], v[228:231], v[68:71]
	v_mfma_f32_16x16x32_bf16 v[116:119], v[192:195], v[208:211], v[116:119]
	v_mfma_f32_16x16x32_bf16 v[108:111], v[200:203], v[208:211], v[108:111]
	v_mfma_f32_16x16x32_bf16 v[100:103], v[192:195], v[216:219], v[100:103]
	v_mfma_f32_16x16x32_bf16 v[92:95], v[200:203], v[216:219], v[92:95]
	v_mfma_f32_16x16x32_bf16 v[84:87], v[192:195], v[224:227], v[84:87]
	v_mfma_f32_16x16x32_bf16 v[76:79], v[200:203], v[224:227], v[76:79]
	v_mfma_f32_16x16x32_bf16 v[72:75], v[192:195], v[232:235], v[72:75]
	v_mfma_f32_16x16x32_bf16 v[68:71], v[200:203], v[232:235], v[68:71]
	s_barrier
	s_add_i32 s38, s39, s28
	v_lshl_add_u64 v[236:237], s[48:49], 0, v[136:137]
	s_mov_b32 m0, s38
	ds_read_b128 v[204:207], v167 offset:16384
	ds_read_b128 v[208:211], v167 offset:17408
	ds_read_b128 v[212:215], v167 offset:18432
	ds_read_b128 v[216:219], v167 offset:19456
	ds_read_b128 v[220:223], v167 offset:20480
	ds_read_b128 v[224:227], v167 offset:21504
	ds_read_b128 v[228:231], v167 offset:22528
	ds_read_b128 v[232:235], v167 offset:23552
	global_load_lds_dwordx4 v[236:237], off
	s_add_i32 m0, s38, 0x2000
	s_add_u32 s38, s48, 0x80000
	v_lshl_add_u64 v[238:239], s[48:49], 0, v[150:151]
	s_addc_u32 s39, s49, 0
	s_add_i32 s20, s20, s28
	global_load_lds_dwordx4 v[238:239], off
	v_lshl_add_u64 v[240:241], s[38:39], 0, v[136:137]
	s_mov_b32 m0, s20
	v_lshl_add_u64 v[242:243], s[50:51], 0, v[152:153]
	global_load_lds_dwordx4 v[240:241], off
	v_lshl_add_u64 v[240:241], s[38:39], 0, v[150:151]
	s_add_i32 m0, s20, 0x2000
	s_nop 0
	global_load_lds_dwordx4 v[240:241], off
	v_lshl_add_u64 v[240:241], s[50:51], 0, v[154:155]
	s_mov_b32 m0, s29
	s_nop 0
	global_load_lds_dwordx4 v[240:241], off
	s_mov_b32 m0, s52
	s_nop 0
	global_load_lds_dwordx4 v[242:243], off
	s_waitcnt vmcnt(8)
	s_waitcnt lgkmcnt(0)
	s_barrier
; #define PG8_STAGE(bufoff, gbase, voff) do { _Pragma("unroll") for (int _i = 0; _i < 2; ++_i) \
;         __builtin_amdgcn_global_load_lds((const unsigned*)((const char*)(gbase) + (voff)[_i]), (PG8_LAS unsigned*)(lds + (bufoff) + ldsw + _i * 8192), 16, 0, 0); } while (0)
; #define PG8_LDA(dst, b, h) do { _Pragma("unroll") for (int m = 0; m < 4; ++m) _Pragma("unroll") for (int k = 0; k < 2; ++k) dst[m][k] = *(const PG8_LAS bf16x8*)(lds + PG8_SA(b, h) + aoff + m * 2048 + k * 1024); } while (0)
; #define PG8_LDB(dst, b, h) do { _Pragma("unroll") for (int n = 0; n < 2; ++n) _Pragma("unroll") for (int k = 0; k < 2; ++k) dst[n][k] = *(const PG8_LAS bf16x8*)(lds + PG8_SB(b, h) + boff + n * 2048 + k * 1024); } while (0)
; #define PG8_MMA(ai, bj, At, Bt) do { __builtin_amdgcn_s_setprio(1); _Pragma("unroll") for (int m = 0; m < 4; ++m) _Pragma("unroll") for (int n = 0; n < 2; ++n) _Pragma("unroll") for (int k = 0; k < 2; ++k) \
;         acc[ai][bj][m][n] = __builtin_amdgcn_mfma_f32_16x16x32_bf16(Bt[n][k], At[m][k], acc[ai][bj][m][n], 0, 0, 0); __builtin_amdgcn_s_setprio(0); } while (0)
; #define PG8_WAIT_V(n) asm volatile("s_waitcnt vmcnt(" #n ")" ::: "memory")
; #define PG8_WAIT_L(n) asm volatile("s_waitcnt lgkmcnt(" #n ")" ::: "memory")
; #define PG8_BAR __builtin_amdgcn_s_barrier()
; #define PG8_SCHED __builtin_amdgcn_sched_barrier(0)
; template <class Epi, class Sched, bool ALIGN_EPI = false, bool SP2 = false>
; __device__ __forceinline__ void gemm_phase(PG8_LAS unsigned char* lds, const Gemm g, const Sched& S, const Epi& E) {
;     ...
;             PG8_WAIT_V(8); PG8_WAIT_L(0); PG8_BAR; PG8_MMA(1, 0, At, B0); PG8_MMA(1, 1, At, B1); PG8_BAR; PG8_SCHED;
;             PG8_LDB(B0, 1, 0); PG8_LDB(B1, 1, 1); PG8_SCHED; PG8_LDA(At, 1, 0); PG8_STAGE(PG8_SA(0, 1), a2 + hstep, voffA);
;             PG8_WAIT_V(8); PG8_WAIT_L(0); PG8_BAR; PG8_MMA(0, 0, At, B0); PG8_MMA(0, 1, At, B1); PG8_BAR; PG8_SCHED;
	s_waitcnt lgkmcnt(0)
	v_mfma_f32_16x16x32_bf16 v[64:67], v[160:163], v[204:207], v[64:67]
	v_mfma_f32_16x16x32_bf16 v[60:63], v[180:183], v[204:207], v[60:63]
	v_mfma_f32_16x16x32_bf16 v[56:59], v[160:163], v[212:215], v[56:59]
	v_mfma_f32_16x16x32_bf16 v[48:51], v[180:183], v[212:215], v[48:51]
	v_mfma_f32_16x16x32_bf16 v[40:43], v[160:163], v[220:223], v[40:43]
	v_mfma_f32_16x16x32_bf16 v[32:35], v[180:183], v[220:223], v[32:35]
	v_mfma_f32_16x16x32_bf16 v[24:27], v[160:163], v[228:231], v[24:27]
	v_mfma_f32_16x16x32_bf16 v[16:19], v[180:183], v[228:231], v[16:19]
	v_mfma_f32_16x16x32_bf16 v[64:67], v[176:179], v[208:211], v[64:67]
	v_mfma_f32_16x16x32_bf16 v[60:63], v[184:187], v[208:211], v[60:63]
	v_mfma_f32_16x16x32_bf16 v[56:59], v[176:179], v[216:219], v[56:59]
	v_mfma_f32_16x16x32_bf16 v[48:51], v[184:187], v[216:219], v[48:51]
	v_mfma_f32_16x16x32_bf16 v[40:43], v[176:179], v[224:227], v[40:43]
	v_mfma_f32_16x16x32_bf16 v[32:35], v[184:187], v[224:227], v[32:35]
	v_mfma_f32_16x16x32_bf16 v[24:27], v[176:179], v[232:235], v[24:27]
	v_mfma_f32_16x16x32_bf16 v[16:19], v[184:187], v[232:235], v[16:19]
	v_mfma_f32_16x16x32_bf16 v[52:55], v[188:191], v[204:207], v[52:55]
	v_mfma_f32_16x16x32_bf16 v[44:47], v[196:199], v[204:207], v[44:47]
	v_mfma_f32_16x16x32_bf16 v[36:39], v[188:191], v[212:215], v[36:39]
	v_mfma_f32_16x16x32_bf16 v[28:31], v[196:199], v[212:215], v[28:31]
	v_mfma_f32_16x16x32_bf16 v[20:23], v[188:191], v[220:223], v[20:23]
	v_mfma_f32_16x16x32_bf16 v[12:15], v[196:199], v[220:223], v[12:15]
	v_mfma_f32_16x16x32_bf16 v[8:11], v[188:191], v[228:231], v[8:11]
	v_mfma_f32_16x16x32_bf16 v[4:7], v[196:199], v[228:231], v[4:7]
	v_mfma_f32_16x16x32_bf16 v[52:55], v[192:195], v[208:211], v[52:55]
	v_mfma_f32_16x16x32_bf16 v[44:47], v[200:203], v[208:211], v[44:47]
	v_mfma_f32_16x16x32_bf16 v[36:39], v[192:195], v[216:219], v[36:39]
	v_mfma_f32_16x16x32_bf16 v[28:31], v[200:203], v[216:219], v[28:31]
	v_mfma_f32_16x16x32_bf16 v[20:23], v[192:195], v[224:227], v[20:23]
	v_mfma_f32_16x16x32_bf16 v[12:15], v[200:203], v[224:227], v[12:15]
	v_mfma_f32_16x16x32_bf16 v[8:11], v[192:195], v[232:235], v[8:11]
	v_mfma_f32_16x16x32_bf16 v[4:7], v[200:203], v[232:235], v[4:7]
	s_barrier
	s_add_i32 s20, 0, 0x18000
	s_add_i32 s76, 0, 0x1c000
	v_add_u32_e32 v184, s20, v165
	v_add_u32_e32 v200, s76, v165
	ds_read_b128 v[160:163], v184
	ds_read_b128 v[176:179], v184 offset:1024
	ds_read_b128 v[180:183], v184 offset:2048
	ds_read_b128 v[184:187], v184 offset:3072
	ds_read_b128 v[188:191], v200
	ds_read_b128 v[192:195], v200 offset:1024
	ds_read_b128 v[196:199], v200 offset:2048
	ds_read_b128 v[200:203], v200 offset:3072
	s_add_u32 s38, s50, 0x80000
	s_addc_u32 s39, s51, 0
	s_mov_b32 m0, s53
	v_lshl_add_u64 v[244:245], s[38:39], 0, v[154:155]
	ds_read_b128 v[204:207], v167 offset:32768
	ds_read_b128 v[208:211], v167 offset:33792
	ds_read_b128 v[212:215], v167 offset:34816
	ds_read_b128 v[216:219], v167 offset:35840
	ds_read_b128 v[220:223], v167 offset:36864
	ds_read_b128 v[224:227], v167 offset:37888
	ds_read_b128 v[228:231], v167 offset:38912
	ds_read_b128 v[232:235], v167 offset:39936
	global_load_lds_dwordx4 v[244:245], off
	v_lshl_add_u64 v[244:245], s[38:39], 0, v[152:153]
	s_mov_b32 m0, s54
	s_nop 0
	global_load_lds_dwordx4 v[244:245], off
	s_waitcnt vmcnt(8)
	s_waitcnt lgkmcnt(0)
	s_barrier
	s_waitcnt lgkmcnt(0)
	v_mfma_f32_16x16x32_bf16 v[128:131], v[160:163], v[204:207], v[128:131]
	v_mfma_f32_16x16x32_bf16 v[124:127], v[180:183], v[204:207], v[124:127]
	v_mfma_f32_16x16x32_bf16 v[120:123], v[160:163], v[212:215], v[120:123]
	v_mfma_f32_16x16x32_bf16 v[112:115], v[180:183], v[212:215], v[112:115]
	v_mfma_f32_16x16x32_bf16 v[104:107], v[160:163], v[220:223], v[104:107]
	v_mfma_f32_16x16x32_bf16 v[96:99], v[180:183], v[220:223], v[96:99]
	v_mfma_f32_16x16x32_bf16 v[88:91], v[160:163], v[228:231], v[88:91]
	v_mfma_f32_16x16x32_bf16 v[80:83], v[180:183], v[228:231], v[80:83]
	v_mfma_f32_16x16x32_bf16 v[128:131], v[176:179], v[208:211], v[128:131]
	v_mfma_f32_16x16x32_bf16 v[124:127], v[184:187], v[208:211], v[124:127]
	v_mfma_f32_16x16x32_bf16 v[120:123], v[176:179], v[216:219], v[120:123]
	v_mfma_f32_16x16x32_bf16 v[112:115], v[184:187], v[216:219], v[112:115]
	v_mfma_f32_16x16x32_bf16 v[104:107], v[176:179], v[224:227], v[104:107]
	v_mfma_f32_16x16x32_bf16 v[96:99], v[184:187], v[224:227], v[96:99]
	v_mfma_f32_16x16x32_bf16 v[88:91], v[176:179], v[232:235], v[88:91]
	v_mfma_f32_16x16x32_bf16 v[80:83], v[184:187], v[232:235], v[80:83]
	v_mfma_f32_16x16x32_bf16 v[116:119], v[188:191], v[204:207], v[116:119]
	v_mfma_f32_16x16x32_bf16 v[108:111], v[196:199], v[204:207], v[108:111]
	v_mfma_f32_16x16x32_bf16 v[100:103], v[188:191], v[212:215], v[100:103]
	v_mfma_f32_16x16x32_bf16 v[92:95], v[196:199], v[212:215], v[92:95]
	v_mfma_f32_16x16x32_bf16 v[84:87], v[188:191], v[220:223], v[84:87]
	v_mfma_f32_16x16x32_bf16 v[76:79], v[196:199], v[220:223], v[76:79]
	v_mfma_f32_16x16x32_bf16 v[72:75], v[188:191], v[228:231], v[72:75]
	v_mfma_f32_16x16x32_bf16 v[68:71], v[196:199], v[228:231], v[68:71]
	v_mfma_f32_16x16x32_bf16 v[116:119], v[192:195], v[208:211], v[116:119]
	v_mfma_f32_16x16x32_bf16 v[108:111], v[200:203], v[208:211], v[108:111]
	v_mfma_f32_16x16x32_bf16 v[100:103], v[192:195], v[216:219], v[100:103]
	v_mfma_f32_16x16x32_bf16 v[92:95], v[200:203], v[216:219], v[92:95]
	v_mfma_f32_16x16x32_bf16 v[84:87], v[192:195], v[224:227], v[84:87]
	v_mfma_f32_16x16x32_bf16 v[76:79], v[200:203], v[224:227], v[76:79]
	v_mfma_f32_16x16x32_bf16 v[72:75], v[192:195], v[232:235], v[72:75]
	v_mfma_f32_16x16x32_bf16 v[68:71], v[200:203], v[232:235], v[68:71]
	s_barrier
; #define PG8_STAGE(bufoff, gbase, voff) do { _Pragma("unroll") for (int _i = 0; _i < 2; ++_i) \
;         __builtin_amdgcn_global_load_lds((const unsigned*)((const char*)(gbase) + (voff)[_i]), (PG8_LAS unsigned*)(lds + (bufoff) + ldsw + _i * 8192), 16, 0, 0); } while (0)
; #define PG8_LDA(dst, b, h) do { _Pragma("unroll") for (int m = 0; m < 4; ++m) _Pragma("unroll") for (int k = 0; k < 2; ++k) dst[m][k] = *(const PG8_LAS bf16x8*)(lds + PG8_SA(b, h) + aoff + m * 2048 + k * 1024); } while (0)
; #define PG8_MMA(ai, bj, At, Bt) do { __builtin_amdgcn_s_setprio(1); _Pragma("unroll") for (int m = 0; m < 4; ++m) _Pragma("unroll") for (int n = 0; n < 2; ++n) _Pragma("unroll") for (int k = 0; k < 2; ++k) \
;         acc[ai][bj][m][n] = __builtin_amdgcn_mfma_f32_16x16x32_bf16(Bt[n][k], At[m][k], acc[ai][bj][m][n], 0, 0, 0); __builtin_amdgcn_s_setprio(0); } while (0)
; #define PG8_WAIT_V(n) asm volatile("s_waitcnt vmcnt(" #n ")" ::: "memory")
; #define PG8_WAIT_L(n) asm volatile("s_waitcnt lgkmcnt(" #n ")" ::: "memory")
; #define PG8_BAR __builtin_amdgcn_s_barrier()
; #define PG8_SCHED __builtin_amdgcn_sched_barrier(0)
; template <class Epi, class Sched, bool ALIGN_EPI = false, bool SP2 = false>
; __device__ __forceinline__ void gemm_phase(PG8_LAS unsigned char* lds, const Gemm g, const Sched& S, const Epi& E) {
;     ...
;         for (int t = 0; t < nt; t += 2) {
;             const bool last = (t == nt - 2);
;     ...
;             PG8_LDA(At, 1, 1); PG8_STAGE(PG8_SB(1, 0), b3, voffB); PG8_STAGE(PG8_SB(1, 1), b3 + hstep, voffB); PG8_STAGE(PG8_SA(1, 0), a3, voffA);
;             PG8_WAIT_V(8); PG8_WAIT_L(0); PG8_BAR; PG8_MMA(1, 0, At, B0); PG8_MMA(1, 1, At, B1); PG8_BAR; PG8_SCHED;
	s_add_i32 s20, s20, s28
	v_lshl_add_u64 v[236:237], v[236:237], 0, s[34:35]
	s_mov_b32 m0, s20
	ds_read_b128 v[204:207], v167 offset:49152
	ds_read_b128 v[208:211], v167 offset:50176
	ds_read_b128 v[212:215], v167 offset:51200
	ds_read_b128 v[216:219], v167 offset:52224
	ds_read_b128 v[220:223], v167 offset:53248
	ds_read_b128 v[224:227], v167 offset:54272
	ds_read_b128 v[228:231], v167 offset:55296
	ds_read_b128 v[232:235], v167 offset:56320
	global_load_lds_dwordx4 v[236:237], off
	s_add_i32 m0, s20, 0x2000
	s_add_u32 s38, s48, 0x80080
	v_lshl_add_u64 v[236:237], v[238:239], 0, s[34:35]
	s_addc_u32 s39, s49, 0
	s_add_i32 s20, s76, s28
	global_load_lds_dwordx4 v[236:237], off
	v_lshl_add_u64 v[236:237], s[38:39], 0, v[136:137]
	s_mov_b32 m0, s20
	s_nop 0
	global_load_lds_dwordx4 v[236:237], off
	v_lshl_add_u64 v[236:237], s[38:39], 0, v[150:151]
	s_add_i32 m0, s20, 0x2000
	s_nop 0
	global_load_lds_dwordx4 v[236:237], off
	v_lshl_add_u64 v[236:237], v[240:241], 0, s[34:35]
	s_mov_b32 m0, s55
	s_nop 0
	global_load_lds_dwordx4 v[236:237], off
	v_lshl_add_u64 v[236:237], v[242:243], 0, s[34:35]
	s_mov_b32 m0, s84
	s_nop 0
	global_load_lds_dwordx4 v[236:237], off
	s_waitcnt vmcnt(8)
	s_waitcnt lgkmcnt(0)
	s_barrier
	s_waitcnt lgkmcnt(0)
	v_mfma_f32_16x16x32_bf16 v[64:67], v[160:163], v[204:207], v[64:67]
	v_mfma_f32_16x16x32_bf16 v[60:63], v[180:183], v[204:207], v[60:63]
	v_mfma_f32_16x16x32_bf16 v[56:59], v[160:163], v[212:215], v[56:59]
	v_mfma_f32_16x16x32_bf16 v[48:51], v[180:183], v[212:215], v[48:51]
	v_mfma_f32_16x16x32_bf16 v[40:43], v[160:163], v[220:223], v[40:43]
	v_mfma_f32_16x16x32_bf16 v[32:35], v[180:183], v[220:223], v[32:35]
	v_mfma_f32_16x16x32_bf16 v[24:27], v[160:163], v[228:231], v[24:27]
	v_mfma_f32_16x16x32_bf16 v[16:19], v[180:183], v[228:231], v[16:19]
	v_mfma_f32_16x16x32_bf16 v[64:67], v[176:179], v[208:211], v[64:67]
	v_mfma_f32_16x16x32_bf16 v[60:63], v[184:187], v[208:211], v[60:63]
	v_mfma_f32_16x16x32_bf16 v[56:59], v[176:179], v[216:219], v[56:59]
	v_mfma_f32_16x16x32_bf16 v[48:51], v[184:187], v[216:219], v[48:51]
	v_mfma_f32_16x16x32_bf16 v[40:43], v[176:179], v[224:227], v[40:43]
	v_mfma_f32_16x16x32_bf16 v[32:35], v[184:187], v[224:227], v[32:35]
	v_mfma_f32_16x16x32_bf16 v[24:27], v[176:179], v[232:235], v[24:27]
	v_mfma_f32_16x16x32_bf16 v[16:19], v[184:187], v[232:235], v[16:19]
	v_mfma_f32_16x16x32_bf16 v[52:55], v[188:191], v[204:207], v[52:55]
	v_mfma_f32_16x16x32_bf16 v[44:47], v[196:199], v[204:207], v[44:47]
	v_mfma_f32_16x16x32_bf16 v[36:39], v[188:191], v[212:215], v[36:39]
	v_mfma_f32_16x16x32_bf16 v[28:31], v[196:199], v[212:215], v[28:31]
	v_mfma_f32_16x16x32_bf16 v[20:23], v[188:191], v[220:223], v[20:23]
	v_mfma_f32_16x16x32_bf16 v[12:15], v[196:199], v[220:223], v[12:15]
	v_mfma_f32_16x16x32_bf16 v[8:11], v[188:191], v[228:231], v[8:11]
	v_mfma_f32_16x16x32_bf16 v[4:7], v[196:199], v[228:231], v[4:7]
	v_mfma_f32_16x16x32_bf16 v[52:55], v[192:195], v[208:211], v[52:55]
	v_mfma_f32_16x16x32_bf16 v[44:47], v[200:203], v[208:211], v[44:47]
	v_mfma_f32_16x16x32_bf16 v[36:39], v[192:195], v[216:219], v[36:39]
	v_mfma_f32_16x16x32_bf16 v[28:31], v[200:203], v[216:219], v[28:31]
	v_mfma_f32_16x16x32_bf16 v[20:23], v[192:195], v[224:227], v[20:23]
	v_mfma_f32_16x16x32_bf16 v[12:15], v[200:203], v[224:227], v[12:15]
	v_mfma_f32_16x16x32_bf16 v[8:11], v[192:195], v[232:235], v[8:11]
	v_mfma_f32_16x16x32_bf16 v[4:7], v[200:203], v[232:235], v[4:7]
	s_barrier
	s_add_i32 s79, s79, 2
	s_add_u32 s46, s46, 0x100
	s_addc_u32 s47, s47, 0
	s_add_u32 s97, s97, 0x100
	s_addc_u32 s78, s78, 0
	s_cmp_gt_u32 s79, 29
	s_cbranch_scc0 .LBB0_352
	s_and_b64 vcc, exec, s[4:5]
	s_cbranch_vccz .LBB0_355
	s_barrier

; #define PG8_STAGE(bufoff, gbase, voff) do { _Pragma("unroll") for (int _i = 0; _i < 2; ++_i) \
;         __builtin_amdgcn_global_load_lds((const unsigned*)((const char*)(gbase) + (voff)[_i]), (PG8_LAS unsigned*)(lds + (bufoff) + ldsw + _i * 8192), 16, 0, 0); } while (0)
; #define PG8_LDA(dst, b, h) do { _Pragma("unroll") for (int m = 0; m < 4; ++m) _Pragma("unroll") for (int k = 0; k < 2; ++k) dst[m][k] = *(const PG8_LAS bf16x8*)(lds + PG8_SA(b, h) + aoff + m * 2048 + k * 1024); } while (0)
; #define PG8_LDB(dst, b, h) do { _Pragma("unroll") for (int n = 0; n < 2; ++n) _Pragma("unroll") for (int k = 0; k < 2; ++k) dst[n][k] = *(const PG8_LAS bf16x8*)(lds + PG8_SB(b, h) + boff + n * 2048 + k * 1024); } while (0)
; #define PG8_WAIT_V(n) asm volatile("s_waitcnt vmcnt(" #n ")" ::: "memory")
; #define PG8_WAIT_L(n) asm volatile("s_waitcnt lgkmcnt(" #n ")" ::: "memory")
; #define PG8_BAR __builtin_amdgcn_s_barrier()
; #define PG8_SCHED __builtin_amdgcn_sched_barrier(0)
; template <class Epi, class Sched, bool ALIGN_EPI = false, bool SP2 = false>
; __device__ __forceinline__ void gemm_phase(PG8_LAS unsigned char* lds, const Gemm g, const Sched& S, const Epi& E) {
;     ...
;         for (int t = 0; t < nt; t += 2) {
;             const bool last = (t == nt - 2);
;             const char* a1 = cA + (size_t)(t + 1) * kstep;
;             const char* a2 = last ? nA : cA + (size_t)(t + 2) * kstep; const char* b2 = last ? nB : cB + (size_t)(t + 2) * kstep;
;             const char* a3 = a2 + kstep; const char* b3 = b2 + kstep;
;             if (last && has_next) S.a_ready(nxt);
;             if (last) E.prefetch(cur, wid, lane, lds + STAGE_BYTES + 1024);
;             if constexpr (SP2) {
;             PG8_LDB(B0, 0, 0); PG8_LDB(B1, 0, 1); PG8_SCHED; PG8_LDA(At, 0, 0); PG8_STAGE(PG8_SA(1, 1), a1 + hstep, voffA);
;             PG8_WAIT_V(8); PG8_WAIT_L(0); PG8_BAR; PG8_MMA(0, 0, At, B0); PG8_MMA(0, 1, At, B1); PG8_BAR; PG8_SCHED;
;             PG8_LDA(At, 0, 1); PG8_STAGE(PG8_SB(0, 0), b2, voffB); PG8_STAGE(PG8_SB(0, 1), b2 + hstep, voffB); PG8_STAGE(PG8_SA(0, 0), a2, voffA);
;             PG8_WAIT_V(8); PG8_WAIT_L(0); PG8_BAR; PG8_MMA(1, 0, At, B0); PG8_MMA(1, 1, At, B1); PG8_BAR; PG8_SCHED;
;             PG8_LDB(B0, 1, 0); PG8_LDB(B1, 1, 1); PG8_SCHED; PG8_LDA(At, 1, 0); PG8_STAGE(PG8_SA(0, 1), a2 + hstep, voffA);
.LBB0_631:
	s_add_u32 s20, s46, 0xfff80080
	s_addc_u32 s38, s47, -1
	s_add_i32 s39, 0, 0x10000
	s_cmp_eq_u32 s79, 28
	s_cselect_b32 s51, s27, s38
	s_cselect_b32 s50, s85, s20
	s_cselect_b32 s49, s25, s78
	s_cselect_b32 s48, s96, s97
	s_add_i32 s20, 0, 0x14000
	v_add_u32_e32 v184, s39, v177
	v_add_u32_e32 v200, s20, v177
	ds_read_b128 v[160:163], v184
	ds_read_b128 v[164:167], v184 offset:1024
	ds_read_b128 v[180:183], v184 offset:2048
	ds_read_b128 v[184:187], v184 offset:3072
	ds_read_b128 v[188:191], v200
	ds_read_b128 v[192:195], v200 offset:1024
	ds_read_b128 v[196:199], v200 offset:2048
	ds_read_b128 v[200:203], v200 offset:3072
	v_lshl_add_u64 v[236:237], s[46:47], 0, v[156:157]
	s_add_i32 m0, s53, 0xc000
	ds_read_b128 v[204:207], v179
	ds_read_b128 v[208:211], v179 offset:1024
	ds_read_b128 v[212:215], v179 offset:2048
	ds_read_b128 v[216:219], v179 offset:3072
	ds_read_b128 v[220:223], v179 offset:4096
	ds_read_b128 v[224:227], v179 offset:5120
	ds_read_b128 v[228:231], v179 offset:6144
	ds_read_b128 v[232:235], v179 offset:7168
	global_load_lds_dwordx4 v[236:237], off
	v_lshl_add_u64 v[236:237], s[46:47], 0, v[158:159]
	s_add_i32 m0, s53, 0xe000
	s_nop 0
	global_load_lds_dwordx4 v[236:237], off
	s_waitcnt vmcnt(8)
	s_waitcnt lgkmcnt(0)
	s_barrier
	s_waitcnt lgkmcnt(0)
	v_mfma_f32_16x16x32_bf16 v[128:131], v[160:163], v[204:207], v[128:131]
	v_mfma_f32_16x16x32_bf16 v[124:127], v[180:183], v[204:207], v[124:127]
	v_mfma_f32_16x16x32_bf16 v[120:123], v[160:163], v[212:215], v[120:123]
	v_mfma_f32_16x16x32_bf16 v[116:119], v[180:183], v[212:215], v[116:119]
	v_mfma_f32_16x16x32_bf16 v[96:99], v[160:163], v[220:223], v[96:99]
	v_mfma_f32_16x16x32_bf16 v[92:95], v[180:183], v[220:223], v[92:95]
	v_mfma_f32_16x16x32_bf16 v[88:91], v[160:163], v[228:231], v[88:91]
	v_mfma_f32_16x16x32_bf16 v[84:87], v[180:183], v[228:231], v[84:87]
	v_mfma_f32_16x16x32_bf16 v[128:131], v[164:167], v[208:211], v[128:131]
	v_mfma_f32_16x16x32_bf16 v[124:127], v[184:187], v[208:211], v[124:127]
	v_mfma_f32_16x16x32_bf16 v[120:123], v[164:167], v[216:219], v[120:123]
	v_mfma_f32_16x16x32_bf16 v[116:119], v[184:187], v[216:219], v[116:119]
	v_mfma_f32_16x16x32_bf16 v[96:99], v[164:167], v[224:227], v[96:99]
	v_mfma_f32_16x16x32_bf16 v[92:95], v[184:187], v[224:227], v[92:95]
	v_mfma_f32_16x16x32_bf16 v[88:91], v[164:167], v[232:235], v[88:91]
	v_mfma_f32_16x16x32_bf16 v[84:87], v[184:187], v[232:235], v[84:87]
	v_mfma_f32_16x16x32_bf16 v[112:115], v[188:191], v[204:207], v[112:115]
	v_mfma_f32_16x16x32_bf16 v[108:111], v[196:199], v[204:207], v[108:111]
	v_mfma_f32_16x16x32_bf16 v[104:107], v[188:191], v[212:215], v[104:107]
	v_mfma_f32_16x16x32_bf16 v[100:103], v[196:199], v[212:215], v[100:103]
	v_mfma_f32_16x16x32_bf16 v[80:83], v[188:191], v[220:223], v[80:83]
	v_mfma_f32_16x16x32_bf16 v[76:79], v[196:199], v[220:223], v[76:79]
	v_mfma_f32_16x16x32_bf16 v[72:75], v[188:191], v[228:231], v[72:75]
	v_mfma_f32_16x16x32_bf16 v[68:71], v[196:199], v[228:231], v[68:71]
	v_mfma_f32_16x16x32_bf16 v[112:115], v[192:195], v[208:211], v[112:115]
	v_mfma_f32_16x16x32_bf16 v[108:111], v[200:203], v[208:211], v[108:111]
	v_mfma_f32_16x16x32_bf16 v[104:107], v[192:195], v[216:219], v[104:107]
	v_mfma_f32_16x16x32_bf16 v[100:103], v[200:203], v[216:219], v[100:103]
	v_mfma_f32_16x16x32_bf16 v[80:83], v[192:195], v[224:227], v[80:83]
	v_mfma_f32_16x16x32_bf16 v[76:79], v[200:203], v[224:227], v[76:79]
	v_mfma_f32_16x16x32_bf16 v[72:75], v[192:195], v[232:235], v[72:75]
	v_mfma_f32_16x16x32_bf16 v[68:71], v[200:203], v[232:235], v[68:71]
	s_barrier
	s_add_i32 s38, s39, s52
	v_lshl_add_u64 v[236:237], s[48:49], 0, v[136:137]
	s_mov_b32 m0, s38
	ds_read_b128 v[204:207], v179 offset:16384
	ds_read_b128 v[208:211], v179 offset:17408
	ds_read_b128 v[212:215], v179 offset:18432
	ds_read_b128 v[216:219], v179 offset:19456
	ds_read_b128 v[220:223], v179 offset:20480
	ds_read_b128 v[224:227], v179 offset:21504
	ds_read_b128 v[228:231], v179 offset:22528
	ds_read_b128 v[232:235], v179 offset:23552
	global_load_lds_dwordx4 v[236:237], off
	s_add_i32 m0, s38, 0x2000
	s_add_u32 s38, s48, 0x80000
	v_lshl_add_u64 v[238:239], s[48:49], 0, v[150:151]
	s_addc_u32 s39, s49, 0
	s_add_i32 s20, s20, s52
	global_load_lds_dwordx4 v[238:239], off
	v_lshl_add_u64 v[240:241], s[38:39], 0, v[136:137]
	s_mov_b32 m0, s20
	v_lshl_add_u64 v[242:243], s[50:51], 0, v[152:153]
	global_load_lds_dwordx4 v[240:241], off
	v_lshl_add_u64 v[240:241], s[38:39], 0, v[150:151]
	s_add_i32 m0, s20, 0x2000
	s_nop 0
	global_load_lds_dwordx4 v[240:241], off
	v_lshl_add_u64 v[240:241], s[50:51], 0, v[154:155]
	s_mov_b32 m0, s53
	s_nop 0
	global_load_lds_dwordx4 v[240:241], off
	s_mov_b32 m0, s54
	s_nop 0
	global_load_lds_dwordx4 v[242:243], off
	s_waitcnt vmcnt(8)
	s_waitcnt lgkmcnt(0)
	s_barrier
; #define PG8_STAGE(bufoff, gbase, voff) do { _Pragma("unroll") for (int _i = 0; _i < 2; ++_i) \
;         __builtin_amdgcn_global_load_lds((const unsigned*)((const char*)(gbase) + (voff)[_i]), (PG8_LAS unsigned*)(lds + (bufoff) + ldsw + _i * 8192), 16, 0, 0); } while (0)
; #define PG8_LDA(dst, b, h) do { _Pragma("unroll") for (int m = 0; m < 4; ++m) _Pragma("unroll") for (int k = 0; k < 2; ++k) dst[m][k] = *(const PG8_LAS bf16x8*)(lds + PG8_SA(b, h) + aoff + m * 2048 + k * 1024); } while (0)
; #define PG8_LDB(dst, b, h) do { _Pragma("unroll") for (int n = 0; n < 2; ++n) _Pragma("unroll") for (int k = 0; k < 2; ++k) dst[n][k] = *(const PG8_LAS bf16x8*)(lds + PG8_SB(b, h) + boff + n * 2048 + k * 1024); } while (0)
; #define PG8_MMA(ai, bj, At, Bt) do { __builtin_amdgcn_s_setprio(1); _Pragma("unroll") for (int m = 0; m < 4; ++m) _Pragma("unroll") for (int n = 0; n < 2; ++n) _Pragma("unroll") for (int k = 0; k < 2; ++k) \
;         acc[ai][bj][m][n] = __builtin_amdgcn_mfma_f32_16x16x32_bf16(Bt[n][k], At[m][k], acc[ai][bj][m][n], 0, 0, 0); __builtin_amdgcn_s_setprio(0); } while (0)
; #define PG8_WAIT_V(n) asm volatile("s_waitcnt vmcnt(" #n ")" ::: "memory")
; #define PG8_WAIT_L(n) asm volatile("s_waitcnt lgkmcnt(" #n ")" ::: "memory")
; #define PG8_BAR __builtin_amdgcn_s_barrier()
; #define PG8_SCHED __builtin_amdgcn_sched_barrier(0)
; template <class Epi, class Sched, bool ALIGN_EPI = false, bool SP2 = false>
; __device__ __forceinline__ void gemm_phase(PG8_LAS unsigned char* lds, const Gemm g, const Sched& S, const Epi& E) {
;     ...
;             PG8_WAIT_V(8); PG8_WAIT_L(0); PG8_BAR; PG8_MMA(1, 0, At, B0); PG8_MMA(1, 1, At, B1); PG8_BAR; PG8_SCHED;
;             PG8_LDB(B0, 1, 0); PG8_LDB(B1, 1, 1); PG8_SCHED; PG8_LDA(At, 1, 0); PG8_STAGE(PG8_SA(0, 1), a2 + hstep, voffA);
;             PG8_WAIT_V(8); PG8_WAIT_L(0); PG8_BAR; PG8_MMA(0, 0, At, B0); PG8_MMA(0, 1, At, B1); PG8_BAR; PG8_SCHED;
	s_waitcnt lgkmcnt(0)
	v_mfma_f32_16x16x32_bf16 v[64:67], v[160:163], v[204:207], v[64:67]
	v_mfma_f32_16x16x32_bf16 v[60:63], v[180:183], v[204:207], v[60:63]
	v_mfma_f32_16x16x32_bf16 v[56:59], v[160:163], v[212:215], v[56:59]
	v_mfma_f32_16x16x32_bf16 v[52:55], v[180:183], v[212:215], v[52:55]
	v_mfma_f32_16x16x32_bf16 v[32:35], v[160:163], v[220:223], v[32:35]
	v_mfma_f32_16x16x32_bf16 v[28:31], v[180:183], v[220:223], v[28:31]
	v_mfma_f32_16x16x32_bf16 v[24:27], v[160:163], v[228:231], v[24:27]
	v_mfma_f32_16x16x32_bf16 v[20:23], v[180:183], v[228:231], v[20:23]
	v_mfma_f32_16x16x32_bf16 v[64:67], v[164:167], v[208:211], v[64:67]
	v_mfma_f32_16x16x32_bf16 v[60:63], v[184:187], v[208:211], v[60:63]
	v_mfma_f32_16x16x32_bf16 v[56:59], v[164:167], v[216:219], v[56:59]
	v_mfma_f32_16x16x32_bf16 v[52:55], v[184:187], v[216:219], v[52:55]
	v_mfma_f32_16x16x32_bf16 v[32:35], v[164:167], v[224:227], v[32:35]
	v_mfma_f32_16x16x32_bf16 v[28:31], v[184:187], v[224:227], v[28:31]
	v_mfma_f32_16x16x32_bf16 v[24:27], v[164:167], v[232:235], v[24:27]
	v_mfma_f32_16x16x32_bf16 v[20:23], v[184:187], v[232:235], v[20:23]
	v_mfma_f32_16x16x32_bf16 v[48:51], v[188:191], v[204:207], v[48:51]
	v_mfma_f32_16x16x32_bf16 v[44:47], v[196:199], v[204:207], v[44:47]
	v_mfma_f32_16x16x32_bf16 v[40:43], v[188:191], v[212:215], v[40:43]
	v_mfma_f32_16x16x32_bf16 v[36:39], v[196:199], v[212:215], v[36:39]
	v_mfma_f32_16x16x32_bf16 v[16:19], v[188:191], v[220:223], v[16:19]
	v_mfma_f32_16x16x32_bf16 v[12:15], v[196:199], v[220:223], v[12:15]
	v_mfma_f32_16x16x32_bf16 v[8:11], v[188:191], v[228:231], v[8:11]
	v_mfma_f32_16x16x32_bf16 v[4:7], v[196:199], v[228:231], v[4:7]
	v_mfma_f32_16x16x32_bf16 v[48:51], v[192:195], v[208:211], v[48:51]
	v_mfma_f32_16x16x32_bf16 v[44:47], v[200:203], v[208:211], v[44:47]
	v_mfma_f32_16x16x32_bf16 v[40:43], v[192:195], v[216:219], v[40:43]
	v_mfma_f32_16x16x32_bf16 v[36:39], v[200:203], v[216:219], v[36:39]
	v_mfma_f32_16x16x32_bf16 v[16:19], v[192:195], v[224:227], v[16:19]
	v_mfma_f32_16x16x32_bf16 v[12:15], v[200:203], v[224:227], v[12:15]
	v_mfma_f32_16x16x32_bf16 v[8:11], v[192:195], v[232:235], v[8:11]
	v_mfma_f32_16x16x32_bf16 v[4:7], v[200:203], v[232:235], v[4:7]
	s_barrier
	s_add_i32 s20, 0, 0x18000
	s_add_i32 s76, 0, 0x1c000
	v_add_u32_e32 v184, s20, v177
	v_add_u32_e32 v200, s76, v177
	ds_read_b128 v[160:163], v184
	ds_read_b128 v[164:167], v184 offset:1024
	ds_read_b128 v[180:183], v184 offset:2048
	ds_read_b128 v[184:187], v184 offset:3072
	ds_read_b128 v[188:191], v200
	ds_read_b128 v[192:195], v200 offset:1024
	ds_read_b128 v[196:199], v200 offset:2048
	ds_read_b128 v[200:203], v200 offset:3072
	s_add_u32 s38, s50, 0x80000
	s_addc_u32 s39, s51, 0
	s_mov_b32 m0, s55
	v_lshl_add_u64 v[244:245], s[38:39], 0, v[154:155]
	ds_read_b128 v[204:207], v179 offset:32768
	ds_read_b128 v[208:211], v179 offset:33792
	ds_read_b128 v[212:215], v179 offset:34816
	ds_read_b128 v[216:219], v179 offset:35840
	ds_read_b128 v[220:223], v179 offset:36864
	ds_read_b128 v[224:227], v179 offset:37888
	ds_read_b128 v[228:231], v179 offset:38912
	ds_read_b128 v[232:235], v179 offset:39936
	global_load_lds_dwordx4 v[244:245], off
	v_lshl_add_u64 v[244:245], s[38:39], 0, v[152:153]
	s_mov_b32 m0, s86
	s_nop 0
	global_load_lds_dwordx4 v[244:245], off
	s_waitcnt vmcnt(8)
	s_waitcnt lgkmcnt(0)
	s_barrier
	s_waitcnt lgkmcnt(0)
	v_mfma_f32_16x16x32_bf16 v[128:131], v[160:163], v[204:207], v[128:131]
	v_mfma_f32_16x16x32_bf16 v[124:127], v[180:183], v[204:207], v[124:127]
	v_mfma_f32_16x16x32_bf16 v[120:123], v[160:163], v[212:215], v[120:123]
	v_mfma_f32_16x16x32_bf16 v[116:119], v[180:183], v[212:215], v[116:119]
	v_mfma_f32_16x16x32_bf16 v[96:99], v[160:163], v[220:223], v[96:99]
	v_mfma_f32_16x16x32_bf16 v[92:95], v[180:183], v[220:223], v[92:95]
	v_mfma_f32_16x16x32_bf16 v[88:91], v[160:163], v[228:231], v[88:91]
	v_mfma_f32_16x16x32_bf16 v[84:87], v[180:183], v[228:231], v[84:87]
	v_mfma_f32_16x16x32_bf16 v[128:131], v[164:167], v[208:211], v[128:131]
	v_mfma_f32_16x16x32_bf16 v[124:127], v[184:187], v[208:211], v[124:127]
	v_mfma_f32_16x16x32_bf16 v[120:123], v[164:167], v[216:219], v[120:123]
	v_mfma_f32_16x16x32_bf16 v[116:119], v[184:187], v[216:219], v[116:119]
	v_mfma_f32_16x16x32_bf16 v[96:99], v[164:167], v[224:227], v[96:99]
	v_mfma_f32_16x16x32_bf16 v[92:95], v[184:187], v[224:227], v[92:95]
	v_mfma_f32_16x16x32_bf16 v[88:91], v[164:167], v[232:235], v[88:91]
	v_mfma_f32_16x16x32_bf16 v[84:87], v[184:187], v[232:235], v[84:87]
	v_mfma_f32_16x16x32_bf16 v[112:115], v[188:191], v[204:207], v[112:115]
	v_mfma_f32_16x16x32_bf16 v[108:111], v[196:199], v[204:207], v[108:111]
	v_mfma_f32_16x16x32_bf16 v[104:107], v[188:191], v[212:215], v[104:107]
	v_mfma_f32_16x16x32_bf16 v[100:103], v[196:199], v[212:215], v[100:103]
	v_mfma_f32_16x16x32_bf16 v[80:83], v[188:191], v[220:223], v[80:83]
	v_mfma_f32_16x16x32_bf16 v[76:79], v[196:199], v[220:223], v[76:79]
	v_mfma_f32_16x16x32_bf16 v[72:75], v[188:191], v[228:231], v[72:75]
	v_mfma_f32_16x16x32_bf16 v[68:71], v[196:199], v[228:231], v[68:71]
	v_mfma_f32_16x16x32_bf16 v[112:115], v[192:195], v[208:211], v[112:115]
	v_mfma_f32_16x16x32_bf16 v[108:111], v[200:203], v[208:211], v[108:111]
	v_mfma_f32_16x16x32_bf16 v[104:107], v[192:195], v[216:219], v[104:107]
	v_mfma_f32_16x16x32_bf16 v[100:103], v[200:203], v[216:219], v[100:103]
	v_mfma_f32_16x16x32_bf16 v[80:83], v[192:195], v[224:227], v[80:83]
	v_mfma_f32_16x16x32_bf16 v[76:79], v[200:203], v[224:227], v[76:79]
	v_mfma_f32_16x16x32_bf16 v[72:75], v[192:195], v[232:235], v[72:75]
	v_mfma_f32_16x16x32_bf16 v[68:71], v[200:203], v[232:235], v[68:71]
	s_barrier
; #define PG8_STAGE(bufoff, gbase, voff) do { _Pragma("unroll") for (int _i = 0; _i < 2; ++_i) \
;         __builtin_amdgcn_global_load_lds((const unsigned*)((const char*)(gbase) + (voff)[_i]), (PG8_LAS unsigned*)(lds + (bufoff) + ldsw + _i * 8192), 16, 0, 0); } while (0)
; #define PG8_LDA(dst, b, h) do { _Pragma("unroll") for (int m = 0; m < 4; ++m) _Pragma("unroll") for (int k = 0; k < 2; ++k) dst[m][k] = *(const PG8_LAS bf16x8*)(lds + PG8_SA(b, h) + aoff + m * 2048 + k * 1024); } while (0)
; #define PG8_MMA(ai, bj, At, Bt) do { __builtin_amdgcn_s_setprio(1); _Pragma("unroll") for (int m = 0; m < 4; ++m) _Pragma("unroll") for (int n = 0; n < 2; ++n) _Pragma("unroll") for (int k = 0; k < 2; ++k) \
;         acc[ai][bj][m][n] = __builtin_amdgcn_mfma_f32_16x16x32_bf16(Bt[n][k], At[m][k], acc[ai][bj][m][n], 0, 0, 0); __builtin_amdgcn_s_setprio(0); } while (0)
; #define PG8_WAIT_V(n) asm volatile("s_waitcnt vmcnt(" #n ")" ::: "memory")
; #define PG8_WAIT_L(n) asm volatile("s_waitcnt lgkmcnt(" #n ")" ::: "memory")
; #define PG8_BAR __builtin_amdgcn_s_barrier()
; #define PG8_SCHED __builtin_amdgcn_sched_barrier(0)
; template <class Epi, class Sched, bool ALIGN_EPI = false, bool SP2 = false>
; __device__ __forceinline__ void gemm_phase(PG8_LAS unsigned char* lds, const Gemm g, const Sched& S, const Epi& E) {
;     ...
;         for (int t = 0; t < nt; t += 2) {
;             const bool last = (t == nt - 2);
;     ...
;             PG8_LDA(At, 1, 1); PG8_STAGE(PG8_SB(1, 0), b3, voffB); PG8_STAGE(PG8_SB(1, 1), b3 + hstep, voffB); PG8_STAGE(PG8_SA(1, 0), a3, voffA);
;             PG8_WAIT_V(8); PG8_WAIT_L(0); PG8_BAR; PG8_MMA(1, 0, At, B0); PG8_MMA(1, 1, At, B1); PG8_BAR; PG8_SCHED;
	s_add_i32 s20, s20, s52
	v_lshl_add_u64 v[236:237], v[236:237], 0, s[34:35]
	s_mov_b32 m0, s20
	ds_read_b128 v[204:207], v179 offset:49152
	ds_read_b128 v[208:211], v179 offset:50176
	ds_read_b128 v[212:215], v179 offset:51200
	ds_read_b128 v[216:219], v179 offset:52224
	ds_read_b128 v[220:223], v179 offset:53248
	ds_read_b128 v[224:227], v179 offset:54272
	ds_read_b128 v[228:231], v179 offset:55296
	ds_read_b128 v[232:235], v179 offset:56320
	global_load_lds_dwordx4 v[236:237], off
	s_add_i32 m0, s20, 0x2000
	s_add_u32 s38, s48, 0x80080
	v_lshl_add_u64 v[236:237], v[238:239], 0, s[34:35]
	s_addc_u32 s39, s49, 0
	s_add_i32 s20, s76, s52
	global_load_lds_dwordx4 v[236:237], off
	v_lshl_add_u64 v[236:237], s[38:39], 0, v[136:137]
	s_mov_b32 m0, s20
	s_nop 0
	global_load_lds_dwordx4 v[236:237], off
	v_lshl_add_u64 v[236:237], s[38:39], 0, v[150:151]
	s_add_i32 m0, s20, 0x2000
	s_nop 0
	global_load_lds_dwordx4 v[236:237], off
	v_lshl_add_u64 v[236:237], v[240:241], 0, s[34:35]
	s_mov_b32 m0, s88
	s_nop 0
	global_load_lds_dwordx4 v[236:237], off
	v_lshl_add_u64 v[236:237], v[242:243], 0, s[34:35]
	s_mov_b32 m0, s89
	s_nop 0
	global_load_lds_dwordx4 v[236:237], off
	s_waitcnt vmcnt(8)
	s_waitcnt lgkmcnt(0)
	s_barrier
	s_waitcnt lgkmcnt(0)
	v_mfma_f32_16x16x32_bf16 v[64:67], v[160:163], v[204:207], v[64:67]
	v_mfma_f32_16x16x32_bf16 v[60:63], v[180:183], v[204:207], v[60:63]
	v_mfma_f32_16x16x32_bf16 v[56:59], v[160:163], v[212:215], v[56:59]
	v_mfma_f32_16x16x32_bf16 v[52:55], v[180:183], v[212:215], v[52:55]
	v_mfma_f32_16x16x32_bf16 v[32:35], v[160:163], v[220:223], v[32:35]
	v_mfma_f32_16x16x32_bf16 v[28:31], v[180:183], v[220:223], v[28:31]
	v_mfma_f32_16x16x32_bf16 v[24:27], v[160:163], v[228:231], v[24:27]
	v_mfma_f32_16x16x32_bf16 v[20:23], v[180:183], v[228:231], v[20:23]
	v_mfma_f32_16x16x32_bf16 v[64:67], v[164:167], v[208:211], v[64:67]
	v_mfma_f32_16x16x32_bf16 v[60:63], v[184:187], v[208:211], v[60:63]
	v_mfma_f32_16x16x32_bf16 v[56:59], v[164:167], v[216:219], v[56:59]
	v_mfma_f32_16x16x32_bf16 v[52:55], v[184:187], v[216:219], v[52:55]
	v_mfma_f32_16x16x32_bf16 v[32:35], v[164:167], v[224:227], v[32:35]
	v_mfma_f32_16x16x32_bf16 v[28:31], v[184:187], v[224:227], v[28:31]
	v_mfma_f32_16x16x32_bf16 v[24:27], v[164:167], v[232:235], v[24:27]
	v_mfma_f32_16x16x32_bf16 v[20:23], v[184:187], v[232:235], v[20:23]
	v_mfma_f32_16x16x32_bf16 v[48:51], v[188:191], v[204:207], v[48:51]
	v_mfma_f32_16x16x32_bf16 v[44:47], v[196:199], v[204:207], v[44:47]
	v_mfma_f32_16x16x32_bf16 v[40:43], v[188:191], v[212:215], v[40:43]
	v_mfma_f32_16x16x32_bf16 v[36:39], v[196:199], v[212:215], v[36:39]
	v_mfma_f32_16x16x32_bf16 v[16:19], v[188:191], v[220:223], v[16:19]
	v_mfma_f32_16x16x32_bf16 v[12:15], v[196:199], v[220:223], v[12:15]
	v_mfma_f32_16x16x32_bf16 v[8:11], v[188:191], v[228:231], v[8:11]
	v_mfma_f32_16x16x32_bf16 v[4:7], v[196:199], v[228:231], v[4:7]
	v_mfma_f32_16x16x32_bf16 v[48:51], v[192:195], v[208:211], v[48:51]
	v_mfma_f32_16x16x32_bf16 v[44:47], v[200:203], v[208:211], v[44:47]
	v_mfma_f32_16x16x32_bf16 v[40:43], v[192:195], v[216:219], v[40:43]
	v_mfma_f32_16x16x32_bf16 v[36:39], v[200:203], v[216:219], v[36:39]
	v_mfma_f32_16x16x32_bf16 v[16:19], v[192:195], v[224:227], v[16:19]
	v_mfma_f32_16x16x32_bf16 v[12:15], v[200:203], v[224:227], v[12:15]
	v_mfma_f32_16x16x32_bf16 v[8:11], v[192:195], v[232:235], v[8:11]
	v_mfma_f32_16x16x32_bf16 v[4:7], v[200:203], v[232:235], v[4:7]
	s_barrier
	s_add_i32 s79, s79, 2
	s_add_u32 s46, s46, 0x100
	s_addc_u32 s47, s47, 0
	s_add_u32 s97, s97, 0x100
	s_addc_u32 s78, s78, 0
	s_cmp_gt_u32 s79, 29
	s_cbranch_scc0 .LBB0_631
	s_and_b64 vcc, exec, s[4:5]
	v_readlane_b32 s96, v247, 43
	v_readlane_b32 s97, v247, 44
	s_cbranch_vccz .LBB0_634
	s_barrier
